# attn: K-frag prefetch + row sums moved into PV gaps; drop redundant vmcnt drains at unit start; decode loop paced with s_sleep 32; P6 epilogue n=1 conv weight loads hoisted
# speedup vs baseline: 1.0125x; 1.0125x over previous
.LBB0_623:
	v_lshl_add_u32 v140, s69, 13, v173
	ds_read_b128 v[42:45], v140
	ds_read_b128 v[46:49], v140 offset:512
	s_cmp_gt_u32 s73, 1
	s_cselect_b64 vcc, -1, 0
	s_waitcnt lgkmcnt(2)
	v_cndmask_b32_e32 v2, 0, v98, vcc
	v_mov_b32_e32 v3, v2
	v_mov_b32_e32 v4, v2
	v_mov_b32_e32 v5, v2
	v_mov_b32_e32 v6, v2
	v_mov_b32_e32 v7, v2
	v_mov_b32_e32 v8, v2
	v_mov_b32_e32 v9, v2
	v_mov_b32_e32 v10, v2
	v_mov_b32_e32 v11, v2
	v_mov_b32_e32 v12, v2
	v_mov_b32_e32 v13, v2
	v_mov_b32_e32 v14, v2
	v_mov_b32_e32 v15, v2
	v_mov_b32_e32 v16, v2
	v_mov_b32_e32 v17, v2
	s_and_b64 vcc, exec, vcc
	s_waitcnt lgkmcnt(1)
	v_mfma_f32_32x32x16_bf16 v[18:33], v[42:45], v[100:103], v[2:17]
	s_waitcnt lgkmcnt(0)
	v_mfma_f32_32x32x16_bf16 v[2:17], v[46:49], v[100:103], v[2:17]
	ds_read_b128 v[42:45], v140 offset:2048
	ds_read_b128 v[46:49], v140 offset:2560
	s_waitcnt lgkmcnt(1)
	v_mfma_f32_32x32x16_bf16 v[18:33], v[42:45], v[104:107], v[18:33]
	s_waitcnt lgkmcnt(0)
	v_mfma_f32_32x32x16_bf16 v[2:17], v[46:49], v[104:107], v[2:17]
	ds_read_b128 v[42:45], v140 offset:4096
	ds_read_b128 v[46:49], v140 offset:4608
	s_waitcnt lgkmcnt(1)
	v_mfma_f32_32x32x16_bf16 v[18:33], v[42:45], v[108:111], v[18:33]
	s_waitcnt lgkmcnt(0)
	v_mfma_f32_32x32x16_bf16 v[2:17], v[46:49], v[108:111], v[2:17]
	ds_read_b128 v[42:45], v140 offset:6144
	ds_read_b128 v[46:49], v140 offset:6656
	s_waitcnt lgkmcnt(1)
	v_mfma_f32_32x32x16_bf16 v[18:33], v[42:45], v[112:115], v[18:33]
	s_waitcnt lgkmcnt(0)
	v_mfma_f32_32x32x16_bf16 v[2:17], v[46:49], v[112:115], v[2:17]
	s_cbranch_vccnz .LBB0_628
	s_or_b32 s22, s74, s66
	v_or_b32_e32 v42, s22, v177
	v_sub_u32_e32 v74, v42, v195
	v_add_u32_e32 v44, -1, v74
	v_med3_i32 v45, v44, 0, v243
	v_med3_i32 v44, v44, 32, v244
	v_lshl_add_u32 v44, v44, 2, s72
	v_add_u32_e32 v46, 0xffffff80, v44
	v_add_u32_e32 v44, -2, v74
	v_med3_i32 v47, v44, 0, v243
	v_med3_i32 v44, v44, 32, v244
	v_lshl_add_u32 v44, v44, 2, s72
	v_add_u32_e32 v48, 0xffffff80, v44
	v_add_u32_e32 v44, -3, v74
	v_med3_i32 v43, v74, 32, v244
	v_med3_i32 v49, v44, 0, v243
	v_med3_i32 v44, v44, 32, v244
	v_med3_i32 v42, v74, 0, v243
	v_lshl_add_u32 v43, v43, 2, s72
	v_lshl_add_u32 v44, v44, 2, s72
	v_lshl_add_u32 v42, v42, 2, s72
	v_add_u32_e32 v43, 0xffffff80, v43
	v_lshl_add_u32 v45, v45, 2, s72
	v_lshl_add_u32 v47, v47, 2, s72
	v_lshl_add_u32 v49, v49, 2, s72
	v_add_u32_e32 v50, 0xffffff80, v44
	ds_read_b32 v42, v42
	ds_read_b32 v44, v43
	ds_read_b32 v43, v45
	ds_read_b32 v45, v46
	ds_read_b32 v46, v47
	ds_read_b32 v48, v48
	ds_read_b32 v47, v49
	ds_read_b32 v49, v50
	v_add_u32_e32 v50, -8, v74
	v_med3_i32 v51, v50, 0, v243
	v_med3_i32 v50, v50, 32, v244
	v_lshl_add_u32 v50, v50, 2, s72
	v_add_u32_e32 v52, 0xffffff80, v50
	v_add_u32_e32 v50, -9, v74
	v_med3_i32 v53, v50, 0, v243
	v_med3_i32 v50, v50, 32, v244
	v_lshl_add_u32 v50, v50, 2, s72
	v_add_u32_e32 v54, 0xffffff80, v50
	v_add_u32_e32 v50, -10, v74
	v_med3_i32 v55, v50, 0, v243
	v_med3_i32 v50, v50, 32, v244
	v_lshl_add_u32 v50, v50, 2, s72
	v_add_u32_e32 v56, 0xffffff80, v50
	v_add_u32_e32 v50, -11, v74
	v_med3_i32 v57, v50, 0, v243
	v_med3_i32 v50, v50, 32, v244
	v_lshl_add_u32 v50, v50, 2, s72
	v_lshl_add_u32 v51, v51, 2, s72
	v_lshl_add_u32 v53, v53, 2, s72
	v_lshl_add_u32 v55, v55, 2, s72
	v_lshl_add_u32 v57, v57, 2, s72
	v_add_u32_e32 v58, 0xffffff80, v50
	ds_read_b32 v50, v51
	ds_read_b32 v52, v52
	ds_read_b32 v51, v53
	ds_read_b32 v53, v54
	ds_read_b32 v54, v55
	ds_read_b32 v56, v56
	ds_read_b32 v55, v57
	ds_read_b32 v57, v58
	v_add_u32_e32 v58, -16, v74
	v_med3_i32 v59, v58, 0, v243
	v_med3_i32 v58, v58, 32, v244
	v_lshl_add_u32 v58, v58, 2, s72
	v_add_u32_e32 v60, 0xffffff80, v58
	v_subrev_u32_e32 v58, 17, v74
	v_med3_i32 v61, v58, 0, v243
	v_med3_i32 v58, v58, 32, v244
	v_lshl_add_u32 v58, v58, 2, s72
	v_add_u32_e32 v62, 0xffffff80, v58
	v_subrev_u32_e32 v58, 18, v74
	v_med3_i32 v63, v58, 0, v243
	v_med3_i32 v58, v58, 32, v244
	v_lshl_add_u32 v58, v58, 2, s72
	v_add_u32_e32 v64, 0xffffff80, v58
	v_subrev_u32_e32 v58, 19, v74
	v_med3_i32 v65, v58, 0, v243
	v_med3_i32 v58, v58, 32, v244
	v_lshl_add_u32 v58, v58, 2, s72
	v_lshl_add_u32 v59, v59, 2, s72
	v_lshl_add_u32 v61, v61, 2, s72
	v_lshl_add_u32 v63, v63, 2, s72
	v_lshl_add_u32 v65, v65, 2, s72
	v_add_u32_e32 v66, 0xffffff80, v58
	ds_read_b32 v58, v59
	ds_read_b32 v60, v60
	ds_read_b32 v59, v61
	ds_read_b32 v61, v62
	ds_read_b32 v62, v63
	ds_read_b32 v64, v64
	ds_read_b32 v63, v65
	ds_read_b32 v65, v66
	v_subrev_u32_e32 v66, 24, v74
	v_med3_i32 v67, v66, 0, v243
	v_med3_i32 v66, v66, 32, v244
	v_lshl_add_u32 v66, v66, 2, s72
	v_add_u32_e32 v68, 0xffffff80, v66
	v_subrev_u32_e32 v66, 25, v74
	v_med3_i32 v69, v66, 0, v243
	v_med3_i32 v66, v66, 32, v244
	v_lshl_add_u32 v66, v66, 2, s72
	v_add_u32_e32 v70, 0xffffff80, v66
	v_subrev_u32_e32 v66, 26, v74
	v_med3_i32 v71, v66, 0, v243
	v_med3_i32 v66, v66, 32, v244
	v_lshl_add_u32 v66, v66, 2, s72
	v_add_u32_e32 v72, 0xffffff80, v66
	v_subrev_u32_e32 v66, 27, v74
	v_med3_i32 v73, v66, 0, v243
	v_med3_i32 v66, v66, 32, v244
	v_lshl_add_u32 v67, v67, 2, s72
	v_lshl_add_u32 v69, v69, 2, s72
	v_lshl_add_u32 v71, v71, 2, s72
	v_lshl_add_u32 v73, v73, 2, s72
	v_lshl_add_u32 v66, v66, 2, s72
	v_add_u32_e32 v75, 0xffffff80, v66
	ds_read_b32 v66, v67
	ds_read_b32 v68, v68
	ds_read_b32 v67, v69
	ds_read_b32 v69, v70
	ds_read_b32 v70, v71
	ds_read_b32 v72, v72
	ds_read_b32 v71, v73
	ds_read_b32 v73, v75
	v_cmp_lt_i32_e32 vcc, 26, v74
	s_waitcnt lgkmcnt(5)
	v_pk_add_f32 v[30:31], v[30:31], v[66:67]
	v_pk_add_f32 v[28:29], v[28:29], v[62:63]
	s_waitcnt lgkmcnt(1)
	v_pk_add_f32 v[32:33], v[32:33], v[70:71]
	v_pk_add_f32 v[26:27], v[26:27], v[58:59]
	v_cndmask_b32_e32 v33, v245, v33, vcc
	v_cmp_lt_i32_e32 vcc, 25, v74
	v_pk_add_f32 v[24:25], v[24:25], v[54:55]
	v_pk_add_f32 v[22:23], v[22:23], v[50:51]
	v_cndmask_b32_e32 v32, v245, v32, vcc
	v_cmp_lt_i32_e32 vcc, 24, v74
	v_pk_add_f32 v[20:21], v[20:21], v[46:47]
	v_pk_add_f32 v[18:19], v[18:19], v[42:43]
	v_cndmask_b32_e32 v31, v245, v31, vcc
	v_cmp_lt_i32_e32 vcc, 23, v74
	s_waitcnt lgkmcnt(0)
	v_pk_add_f32 v[16:17], v[16:17], v[72:73]
	v_pk_add_f32 v[14:15], v[14:15], v[68:69]
	v_cndmask_b32_e32 v30, v245, v30, vcc
	v_cmp_lt_i32_e32 vcc, 18, v74
	v_pk_add_f32 v[12:13], v[12:13], v[64:65]
	v_pk_add_f32 v[10:11], v[10:11], v[60:61]
	v_cndmask_b32_e32 v29, v245, v29, vcc
	v_cmp_lt_i32_e32 vcc, 17, v74
	v_pk_add_f32 v[8:9], v[8:9], v[56:57]
	v_pk_add_f32 v[6:7], v[6:7], v[52:53]
	v_cndmask_b32_e32 v28, v245, v28, vcc
	v_cmp_lt_i32_e32 vcc, 16, v74
	v_pk_add_f32 v[4:5], v[4:5], v[48:49]
	s_waitcnt lgkmcnt(0)
	v_pk_add_f32 v[2:3], v[2:3], v[44:45]
	v_cndmask_b32_e32 v27, v245, v27, vcc
	v_cmp_lt_i32_e32 vcc, 15, v74
	s_nop 1
	v_cndmask_b32_e32 v26, v245, v26, vcc
	v_cmp_lt_i32_e32 vcc, 10, v74
	s_nop 1
	v_cndmask_b32_e32 v25, v245, v25, vcc
	v_cmp_lt_i32_e32 vcc, 9, v74
	s_nop 1
	v_cndmask_b32_e32 v24, v245, v24, vcc
	v_cmp_lt_i32_e32 vcc, 8, v74
	s_nop 1
	v_cndmask_b32_e32 v23, v245, v23, vcc
	v_cmp_lt_i32_e32 vcc, 7, v74
	s_nop 1
	v_cndmask_b32_e32 v22, v245, v22, vcc
	v_cmp_lt_i32_e32 vcc, 2, v74
	s_nop 1
	v_cndmask_b32_e32 v21, v245, v21, vcc
	v_cmp_lt_i32_e32 vcc, 1, v74
	s_nop 1
	v_cndmask_b32_e32 v20, v245, v20, vcc
	v_cmp_lt_i32_e32 vcc, 0, v74
	s_nop 1
	v_cndmask_b32_e32 v19, v245, v19, vcc
	v_cmp_lt_i32_e32 vcc, -1, v74
	s_nop 1
	v_cndmask_b32_e32 v18, v245, v18, vcc
	v_cmp_lt_i32_e32 vcc, 58, v74
	s_nop 1
	v_cndmask_b32_e32 v17, v245, v17, vcc
	v_cmp_lt_i32_e32 vcc, 57, v74
	s_nop 1
	v_cndmask_b32_e32 v16, v245, v16, vcc
	v_cmp_lt_i32_e32 vcc, 56, v74
	s_nop 1
	v_cndmask_b32_e32 v15, v245, v15, vcc
	v_cmp_lt_i32_e32 vcc, 55, v74
	s_nop 1
	v_cndmask_b32_e32 v14, v245, v14, vcc
	v_cmp_lt_i32_e32 vcc, 50, v74
	s_nop 1
	v_cndmask_b32_e32 v13, v245, v13, vcc
	v_cmp_lt_i32_e32 vcc, 49, v74
	s_nop 1
	v_cndmask_b32_e32 v12, v245, v12, vcc
	v_cmp_lt_i32_e32 vcc, 48, v74
	s_nop 1
	v_cndmask_b32_e32 v11, v245, v11, vcc
	v_cmp_lt_i32_e32 vcc, 47, v74
	s_nop 1
	v_cndmask_b32_e32 v10, v245, v10, vcc
	v_cmp_lt_i32_e32 vcc, 42, v74
	s_nop 1
	v_cndmask_b32_e32 v9, v245, v9, vcc
	v_cmp_lt_i32_e32 vcc, 41, v74
	s_nop 1
	v_cndmask_b32_e32 v8, v245, v8, vcc
	v_cmp_lt_i32_e32 vcc, 40, v74
	s_nop 1
	v_cndmask_b32_e32 v7, v245, v7, vcc
	v_cmp_lt_i32_e32 vcc, 39, v74
	s_nop 1
	v_cndmask_b32_e32 v6, v245, v6, vcc
	v_cmp_lt_i32_e32 vcc, 34, v74
	s_nop 1
	v_cndmask_b32_e32 v5, v245, v5, vcc
	v_cmp_lt_i32_e32 vcc, 33, v74
	s_nop 1
	v_cndmask_b32_e32 v4, v245, v4, vcc
	v_cmp_lt_i32_e32 vcc, 32, v74
	s_nop 1
	v_cndmask_b32_e32 v3, v245, v3, vcc
	v_cmp_lt_i32_e32 vcc, 31, v74
	s_nop 1
	v_cndmask_b32_e32 v2, v245, v2, vcc
	s_and_b64 vcc, exec, s[18:19]
	s_mov_b64 s[18:19], -1
	s_cbranch_vccz .LBB0_629

; __device__ __forceinline__ void attn_unit(int b, int h, int qb, const bf16* Q, const bf16* K, const bf16* V, bf16* MIX, LAS unsigned char* lds, const LAS float* BLh, float lam, LAS float* als, gu32* rdy4) {
;     ...
;     for (int t = 1; t < NT; ++t) {
;         ATT_QK(t);
;         const int vb = (int)(lds0 + L_V + pslot * SLOT) + ((lane >> 4) & 1) * 32 + (lane & 3) * 8 + (4 * hi + ((lane & 15) >> 2)) * 64;
.LBB0_633:
	s_lshl_b32 s75, s19, 14
	v_add_u32_e32 v143, s75, v140
	ds_read_b128 v[144:147], v143
	ds_read_b128 v[148:151], v143 offset:512
	ds_read_b128 v[152:155], v143 offset:2048
	ds_read_b128 v[156:159], v143 offset:2560
	ds_read_b128 v[160:163], v143 offset:4096
	ds_read_b128 v[164:167], v143 offset:4608
	ds_read_b128 v[168:171], v143 offset:6144
	ds_read_b128 v[248:251], v143 offset:6656
	s_cmp_lt_i32 s74, s22
	s_cselect_b64 vcc, -1, 0
	v_cndmask_b32_e32 v66, 0, v98, vcc
	v_mov_b32_e32 v67, v66
	v_mov_b32_e32 v68, v66
	v_mov_b32_e32 v69, v66
	v_mov_b32_e32 v70, v66
	v_mov_b32_e32 v71, v66
	v_mov_b32_e32 v72, v66
	v_mov_b32_e32 v73, v66
	v_mov_b32_e32 v74, v66
	v_mov_b32_e32 v75, v66
	v_mov_b32_e32 v76, v66
	v_mov_b32_e32 v77, v66
	v_mov_b32_e32 v78, v66
	v_mov_b32_e32 v79, v66
	v_mov_b32_e32 v80, v66
	v_mov_b32_e32 v81, v66
	s_mov_b32 s76, s19
	s_and_b64 vcc, exec, vcc
	s_waitcnt lgkmcnt(7)
	v_mfma_f32_32x32x16_bf16 v[82:97], v[144:147], v[100:103], v[66:81]
	s_waitcnt lgkmcnt(6)
	v_mfma_f32_32x32x16_bf16 v[66:81], v[148:151], v[100:103], v[66:81]
	s_waitcnt lgkmcnt(5)
	v_mfma_f32_32x32x16_bf16 v[82:97], v[152:155], v[104:107], v[82:97]
	s_waitcnt lgkmcnt(4)
	v_mfma_f32_32x32x16_bf16 v[66:81], v[156:159], v[104:107], v[66:81]
	s_waitcnt lgkmcnt(3)
	v_mfma_f32_32x32x16_bf16 v[82:97], v[160:163], v[108:111], v[82:97]
	s_waitcnt lgkmcnt(2)
	v_mfma_f32_32x32x16_bf16 v[66:81], v[164:167], v[108:111], v[66:81]
	s_waitcnt lgkmcnt(1)
	v_mfma_f32_32x32x16_bf16 v[82:97], v[168:171], v[112:115], v[82:97]
	s_waitcnt lgkmcnt(0)
	v_mfma_f32_32x32x16_bf16 v[66:81], v[248:251], v[112:115], v[66:81]
	s_cbranch_vccnz .LBB0_635
	v_add_u32_e32 v146, 26, v142
	v_med3_i32 v147, v146, 0, v243
	v_med3_i32 v146, v146, 32, v244
	v_lshl_add_u32 v146, v146, 2, s72
	v_add_u32_e32 v148, 0xffffff80, v146
	v_add_u32_e32 v146, 25, v142
	v_med3_i32 v149, v146, 0, v243
	v_med3_i32 v146, v146, 32, v244
	v_lshl_add_u32 v146, v146, 2, s72
	v_add_u32_e32 v143, 27, v142
	v_add_u32_e32 v150, 0xffffff80, v146
	v_add_u32_e32 v146, 24, v142
	v_med3_i32 v145, v143, 32, v244
	v_med3_i32 v151, v146, 0, v243
	v_med3_i32 v146, v146, 32, v244
	v_med3_i32 v144, v143, 0, v243
	v_lshl_add_u32 v145, v145, 2, s72
	v_lshl_add_u32 v146, v146, 2, s72
	v_lshl_add_u32 v144, v144, 2, s72
	v_add_u32_e32 v145, 0xffffff80, v145
	v_lshl_add_u32 v147, v147, 2, s72
	v_lshl_add_u32 v149, v149, 2, s72
	v_lshl_add_u32 v151, v151, 2, s72
	v_add_u32_e32 v152, 0xffffff80, v146
	ds_read_b32 v144, v144
	ds_read_b32 v146, v145
	ds_read_b32 v145, v147
	ds_read_b32 v147, v148
	ds_read_b32 v148, v149
	ds_read_b32 v150, v150
	ds_read_b32 v149, v151
	ds_read_b32 v151, v152
	v_add_u32_e32 v152, 19, v142
	v_med3_i32 v153, v152, 0, v243
	v_med3_i32 v152, v152, 32, v244
	v_lshl_add_u32 v152, v152, 2, s72
	v_add_u32_e32 v154, 0xffffff80, v152
	v_add_u32_e32 v152, 18, v142
	v_med3_i32 v155, v152, 0, v243
	v_med3_i32 v152, v152, 32, v244
	v_lshl_add_u32 v152, v152, 2, s72
	v_add_u32_e32 v156, 0xffffff80, v152
	v_add_u32_e32 v152, 17, v142
	v_med3_i32 v157, v152, 0, v243
	v_med3_i32 v152, v152, 32, v244
	v_lshl_add_u32 v152, v152, 2, s72
	v_add_u32_e32 v158, 0xffffff80, v152
	v_add_u32_e32 v152, 16, v142
	v_med3_i32 v159, v152, 0, v243
	v_med3_i32 v152, v152, 32, v244
	v_lshl_add_u32 v152, v152, 2, s72
	v_lshl_add_u32 v153, v153, 2, s72
	v_lshl_add_u32 v155, v155, 2, s72
	v_lshl_add_u32 v157, v157, 2, s72
	v_lshl_add_u32 v159, v159, 2, s72
	v_add_u32_e32 v160, 0xffffff80, v152
	ds_read_b32 v152, v153
	ds_read_b32 v154, v154
	ds_read_b32 v153, v155
	ds_read_b32 v155, v156
	ds_read_b32 v156, v157
	ds_read_b32 v158, v158
	ds_read_b32 v157, v159
	ds_read_b32 v159, v160
	v_add_u32_e32 v160, 11, v142
	v_med3_i32 v161, v160, 0, v243
	v_med3_i32 v160, v160, 32, v244
	v_lshl_add_u32 v160, v160, 2, s72
	v_add_u32_e32 v162, 0xffffff80, v160
	v_add_u32_e32 v160, 10, v142
	v_med3_i32 v163, v160, 0, v243
	v_med3_i32 v160, v160, 32, v244
	v_lshl_add_u32 v160, v160, 2, s72
	v_add_u32_e32 v164, 0xffffff80, v160
	v_add_u32_e32 v160, 9, v142
	v_med3_i32 v165, v160, 0, v243
	v_med3_i32 v160, v160, 32, v244
	v_lshl_add_u32 v160, v160, 2, s72
	v_add_u32_e32 v166, 0xffffff80, v160
	v_add_u32_e32 v160, 8, v142
	v_med3_i32 v167, v160, 0, v243
	v_med3_i32 v160, v160, 32, v244
	v_lshl_add_u32 v160, v160, 2, s72
	v_lshl_add_u32 v161, v161, 2, s72
	v_lshl_add_u32 v163, v163, 2, s72
	v_lshl_add_u32 v165, v165, 2, s72
	v_lshl_add_u32 v167, v167, 2, s72
	v_add_u32_e32 v168, 0xffffff80, v160
	ds_read_b32 v160, v161
	ds_read_b32 v162, v162
	ds_read_b32 v161, v163
	ds_read_b32 v163, v164
	ds_read_b32 v164, v165
	ds_read_b32 v166, v166
	ds_read_b32 v165, v167
	ds_read_b32 v167, v168
	v_add_u32_e32 v168, 3, v142
	v_med3_i32 v169, v168, 0, v243
	v_med3_i32 v168, v168, 32, v244
	v_lshl_add_u32 v168, v168, 2, s72
	v_add_u32_e32 v170, 0xffffff80, v168
	v_add_u32_e32 v168, 2, v142
	v_med3_i32 v171, v168, 0, v243
	v_med3_i32 v168, v168, 32, v244
	v_lshl_add_u32 v168, v168, 2, s72
	v_add_u32_e32 v213, 0xffffff80, v168
	v_add_u32_e32 v168, 1, v142
	v_med3_i32 v215, v168, 0, v243
	v_med3_i32 v168, v168, 32, v244
	v_lshl_add_u32 v168, v168, 2, s72
	v_add_u32_e32 v217, 0xffffff80, v168
	v_med3_i32 v168, v142, 0, v243
	v_lshl_add_u32 v219, v168, 2, s72
	v_med3_i32 v168, v142, 32, v244
	v_lshl_add_u32 v169, v169, 2, s72
	v_lshl_add_u32 v171, v171, 2, s72
	v_lshl_add_u32 v168, v168, 2, s72
	v_lshl_add_u32 v215, v215, 2, s72
	v_add_u32_e32 v221, 0xffffff80, v168
	ds_read_b32 v168, v169
	ds_read_b32 v170, v170
	ds_read_b32 v169, v171
	ds_read_b32 v171, v213
	ds_read_b32 v248, v215
	ds_read_b32 v250, v217
	ds_read_b32 v249, v219
	ds_read_b32 v251, v221
	v_cmp_lt_i32_e32 vcc, 26, v143
	s_waitcnt lgkmcnt(5)
	v_pk_add_f32 v[94:95], v[94:95], v[168:169]
	v_pk_add_f32 v[92:93], v[92:93], v[164:165]
	s_waitcnt lgkmcnt(1)
	v_pk_add_f32 v[96:97], v[96:97], v[248:249]
	v_pk_add_f32 v[90:91], v[90:91], v[160:161]
	v_cndmask_b32_e32 v97, v245, v97, vcc
	v_cmp_lt_i32_e32 vcc, 25, v143
	v_pk_add_f32 v[88:89], v[88:89], v[156:157]
	v_pk_add_f32 v[86:87], v[86:87], v[152:153]
	v_cndmask_b32_e32 v96, v245, v96, vcc
	v_cmp_lt_i32_e32 vcc, 24, v143
	v_pk_add_f32 v[84:85], v[84:85], v[148:149]
	v_pk_add_f32 v[82:83], v[82:83], v[144:145]
	v_cndmask_b32_e32 v95, v245, v95, vcc
	v_cmp_lt_i32_e32 vcc, 23, v143
	s_waitcnt lgkmcnt(0)
	v_pk_add_f32 v[80:81], v[80:81], v[250:251]
	v_pk_add_f32 v[78:79], v[78:79], v[170:171]
	v_cndmask_b32_e32 v94, v245, v94, vcc
	v_cmp_lt_i32_e32 vcc, 18, v143
	v_pk_add_f32 v[76:77], v[76:77], v[166:167]
	v_pk_add_f32 v[74:75], v[74:75], v[162:163]
	v_cndmask_b32_e32 v93, v245, v93, vcc
	v_cmp_lt_i32_e32 vcc, 17, v143
	v_pk_add_f32 v[72:73], v[72:73], v[158:159]
	v_pk_add_f32 v[70:71], v[70:71], v[154:155]
	v_cndmask_b32_e32 v92, v245, v92, vcc
	v_cmp_lt_i32_e32 vcc, 16, v143
	v_pk_add_f32 v[68:69], v[68:69], v[150:151]
	s_waitcnt lgkmcnt(0)
	v_pk_add_f32 v[66:67], v[66:67], v[146:147]
	v_cndmask_b32_e32 v91, v245, v91, vcc
	v_cmp_lt_i32_e32 vcc, 15, v143
	s_nop 1
	v_cndmask_b32_e32 v90, v245, v90, vcc
	v_cmp_lt_i32_e32 vcc, 10, v143
	s_nop 1
	v_cndmask_b32_e32 v89, v245, v89, vcc
	v_cmp_lt_i32_e32 vcc, 9, v143
	s_nop 1
	v_cndmask_b32_e32 v88, v245, v88, vcc
	v_cmp_lt_i32_e32 vcc, 8, v143
	s_nop 1
	v_cndmask_b32_e32 v87, v245, v87, vcc
	v_cmp_lt_i32_e32 vcc, 7, v143
	s_nop 1
	v_cndmask_b32_e32 v86, v245, v86, vcc
	v_cmp_lt_i32_e32 vcc, 2, v143
	s_nop 1
	v_cndmask_b32_e32 v85, v245, v85, vcc
	v_cmp_lt_i32_e32 vcc, 1, v143
	s_nop 1
	v_cndmask_b32_e32 v84, v245, v84, vcc
	v_cmp_lt_i32_e32 vcc, 0, v143
	s_nop 1
	v_cndmask_b32_e32 v83, v245, v83, vcc
	v_cmp_lt_i32_e32 vcc, -1, v143
	s_nop 1
	v_cndmask_b32_e32 v82, v245, v82, vcc
	v_cmp_lt_i32_e32 vcc, 58, v143
	s_nop 1
	v_cndmask_b32_e32 v81, v245, v81, vcc
	v_cmp_lt_i32_e32 vcc, 57, v143
	s_nop 1
	v_cndmask_b32_e32 v80, v245, v80, vcc
	v_cmp_lt_i32_e32 vcc, 56, v143
	s_nop 1
	v_cndmask_b32_e32 v79, v245, v79, vcc
	v_cmp_lt_i32_e32 vcc, 55, v143
	s_nop 1
	v_cndmask_b32_e32 v78, v245, v78, vcc
	v_cmp_lt_i32_e32 vcc, 50, v143
	s_nop 1
	v_cndmask_b32_e32 v77, v245, v77, vcc
	v_cmp_lt_i32_e32 vcc, 49, v143
	s_nop 1
	v_cndmask_b32_e32 v76, v245, v76, vcc
	v_cmp_lt_i32_e32 vcc, 48, v143
	s_nop 1
	v_cndmask_b32_e32 v75, v245, v75, vcc
	v_cmp_lt_i32_e32 vcc, 47, v143
	s_nop 1
	v_cndmask_b32_e32 v74, v245, v74, vcc
	v_cmp_lt_i32_e32 vcc, 42, v143
	s_nop 1
	v_cndmask_b32_e32 v73, v245, v73, vcc
	v_cmp_lt_i32_e32 vcc, 41, v143
	s_nop 1
	v_cndmask_b32_e32 v72, v245, v72, vcc
	v_cmp_lt_i32_e32 vcc, 40, v143
	s_nop 1
	v_cndmask_b32_e32 v71, v245, v71, vcc
	v_cmp_lt_i32_e32 vcc, 39, v143
	s_nop 1
	v_cndmask_b32_e32 v70, v245, v70, vcc
	v_cmp_lt_i32_e32 vcc, 34, v143
	s_nop 1
	v_cndmask_b32_e32 v69, v245, v69, vcc
	v_cmp_lt_i32_e32 vcc, 33, v143
	s_nop 1
	v_cndmask_b32_e32 v68, v245, v68, vcc
	v_cmp_lt_i32_e32 vcc, 32, v143
	s_nop 1
	v_cndmask_b32_e32 v67, v245, v67, vcc
	v_cmp_lt_i32_e32 vcc, 31, v143
	s_nop 1
	v_cndmask_b32_e32 v66, v245, v66, vcc
.LBB0_635:
	v_lshl_add_u32 v143, s18, 14, v201
	ds_read_b64_tr_b16 v[144:145],v143 offset:0
	ds_read_b64_tr_b16 v[146:147],v143 offset:512
	ds_read_b64_tr_b16 v[148:149],v143 offset:4096
	ds_read_b64_tr_b16 v[150:151],v143 offset:4608
	ds_read_b64_tr_b16 v[152:153],v143 offset:8192
	ds_read_b64_tr_b16 v[154:155],v143 offset:8704
	ds_read_b64_tr_b16 v[156:157],v143 offset:12288
	ds_read_b64_tr_b16 v[158:159],v143 offset:12800
	ds_read_b64_tr_b16 v[160:161],v143 offset:1024
	ds_read_b64_tr_b16 v[162:163],v143 offset:1536
	ds_read_b64_tr_b16 v[164:165],v143 offset:5120
	ds_read_b64_tr_b16 v[166:167],v143 offset:5632
	ds_read_b64_tr_b16 v[168:169],v143 offset:9216
	ds_read_b64_tr_b16 v[170:171],v143 offset:9728
	ds_read_b64_tr_b16 v[248:249],v143 offset:13312
	ds_read_b64_tr_b16 v[250:251],v143 offset:13824
	s_nop 0
	s_waitcnt lgkmcnt(8)
	s_nop 6
	v_exp_f32_e32 v82, v82
	v_mfma_f32_32x32x16_bf16 v[50:65], v[128:131], v[144:147], v[50:65]
	v_exp_f32_e32 v66, v66
	v_mfma_f32_32x32x16_bf16 v[34:49], v[128:131], v[148:151], v[34:49]
	v_exp_f32_e32 v83, v83
	v_exp_f32_e32 v67, v67
	v_add_f32_e32 v253, v82, v66
	v_add_f32_e32 v252, 0, v253
	v_mfma_f32_32x32x16_bf16 v[18:33], v[128:131], v[152:155], v[18:33]
	v_exp_f32_e32 v84, v84
	v_exp_f32_e32 v68, v68
	v_add_f32_e32 v253, v83, v67
	v_add_f32_e32 v252, v253, v252
	v_mfma_f32_32x32x16_bf16 v[2:17], v[128:131], v[156:159], v[2:17]
	v_exp_f32_e32 v85, v85
	v_exp_f32_e32 v69, v69
	v_add_f32_e32 v253, v84, v68
	v_add_f32_e32 v252, v253, v252
	v_add_f32_e32 v253, v85, v69
	v_add_f32_e32 v252, v253, v252
	ds_read_b64_tr_b16 v[128:129],v143 offset:2048
	ds_read_b64_tr_b16 v[130:131],v143 offset:2560
	ds_read_b64_tr_b16 v[144:145],v143 offset:6144
	ds_read_b64_tr_b16 v[146:147],v143 offset:6656
	ds_read_b64_tr_b16 v[148:149],v143 offset:10240
	ds_read_b64_tr_b16 v[150:151],v143 offset:10752
	ds_read_b64_tr_b16 v[152:153],v143 offset:14336
	ds_read_b64_tr_b16 v[154:155],v143 offset:14848
	s_waitcnt lgkmcnt(8)
	s_nop 0
	v_exp_f32_e32 v86, v86
	v_mfma_f32_32x32x16_bf16 v[50:65], v[124:127], v[160:163], v[50:65]
	v_exp_f32_e32 v70, v70
	v_mfma_f32_32x32x16_bf16 v[34:49], v[124:127], v[164:167], v[34:49]
	v_exp_f32_e32 v87, v87
	v_exp_f32_e32 v71, v71
	v_add_f32_e32 v253, v86, v70
	v_add_f32_e32 v252, v253, v252
	v_mfma_f32_32x32x16_bf16 v[18:33], v[124:127], v[168:171], v[18:33]
	v_exp_f32_e32 v88, v88
	v_exp_f32_e32 v72, v72
	v_add_f32_e32 v253, v87, v71
	v_add_f32_e32 v252, v253, v252
	v_mfma_f32_32x32x16_bf16 v[2:17], v[124:127], v[248:251], v[2:17]
	v_exp_f32_e32 v89, v89
	v_exp_f32_e32 v73, v73
	v_add_f32_e32 v253, v88, v72
	v_add_f32_e32 v252, v253, v252
	v_add_f32_e32 v253, v89, v73
	v_add_f32_e32 v252, v253, v252
	ds_read_b64_tr_b16 v[124:125],v143 offset:3072
	ds_read_b64_tr_b16 v[126:127],v143 offset:3584
	ds_read_b64_tr_b16 v[156:157],v143 offset:7168
	ds_read_b64_tr_b16 v[158:159],v143 offset:7680
	ds_read_b64_tr_b16 v[160:161],v143 offset:11264
	ds_read_b64_tr_b16 v[162:163],v143 offset:11776
	ds_read_b64_tr_b16 v[164:165],v143 offset:15360
	ds_read_b64_tr_b16 v[166:167],v143 offset:15872
	s_waitcnt lgkmcnt(8)
	s_nop 0
	v_exp_f32_e32 v90, v90
	v_mfma_f32_32x32x16_bf16 v[50:65], v[120:123], v[128:131], v[50:65]
	v_exp_f32_e32 v74, v74
	v_mfma_f32_32x32x16_bf16 v[34:49], v[120:123], v[144:147], v[34:49]
	v_exp_f32_e32 v91, v91
	v_exp_f32_e32 v75, v75
	v_add_f32_e32 v253, v90, v74
	v_add_f32_e32 v252, v253, v252
	v_mfma_f32_32x32x16_bf16 v[18:33], v[120:123], v[148:151], v[18:33]
	v_exp_f32_e32 v92, v92
	v_exp_f32_e32 v76, v76
	v_add_f32_e32 v253, v91, v75
	v_add_f32_e32 v252, v253, v252
	v_mfma_f32_32x32x16_bf16 v[2:17], v[120:123], v[152:155], v[2:17]
	v_exp_f32_e32 v93, v93
	v_exp_f32_e32 v77, v77
	v_add_f32_e32 v253, v92, v76
	v_add_f32_e32 v252, v253, v252
	v_add_f32_e32 v253, v93, v77
	v_add_f32_e32 v252, v253, v252
	s_waitcnt lgkmcnt(0)
	s_nop 0
	v_exp_f32_e32 v94, v94
	v_mfma_f32_32x32x16_bf16 v[50:65], v[116:119], v[124:127], v[50:65]
	v_exp_f32_e32 v78, v78
	v_mfma_f32_32x32x16_bf16 v[34:49], v[116:119], v[156:159], v[34:49]
	v_exp_f32_e32 v95, v95
	v_exp_f32_e32 v79, v79
	v_add_f32_e32 v253, v94, v78
	v_add_f32_e32 v252, v253, v252
	v_mfma_f32_32x32x16_bf16 v[18:33], v[116:119], v[160:163], v[18:33]
	v_exp_f32_e32 v96, v96
	v_exp_f32_e32 v80, v80
	v_add_f32_e32 v253, v95, v79
	v_add_f32_e32 v252, v253, v252
	v_mfma_f32_32x32x16_bf16 v[2:17], v[116:119], v[164:167], v[2:17]
	v_exp_f32_e32 v97, v97
	v_exp_f32_e32 v81, v81
	v_add_f32_e32 v253, v96, v80
	v_add_f32_e32 v252, v253, v252
	v_add_f32_e32 v253, v97, v81
	v_add_f32_e32 v252, v253, v252
	s_cmp_ge_u32 s74, s21
	s_mov_b64 s[18:19], -1
	s_cbranch_scc0 .LBB0_641
	s_waitcnt vmcnt(0) lgkmcnt(0)
	s_barrier
	s_cbranch_execz .LBB0_642

.LBB0_639:
	v_add_f32_e32 v141, v141, v252
	s_add_i32 s19, s76, 1
	s_cmp_lg_u32 s76, 3
	s_cselect_b32 s19, s19, 0
	s_add_i32 s74, s18, -2
	v_cvt_pk_bf16_f32 v128, v82, v83
	v_cvt_pk_bf16_f32 v129, v84, v85
	v_cvt_pk_bf16_f32 v130, v86, v87
	v_cvt_pk_bf16_f32 v131, v88, v89
	v_cvt_pk_bf16_f32 v124, v90, v91
	v_cvt_pk_bf16_f32 v125, v92, v93
	v_cvt_pk_bf16_f32 v126, v94, v95
	v_cvt_pk_bf16_f32 v127, v96, v97
	v_cvt_pk_bf16_f32 v120, v66, v67
	v_cvt_pk_bf16_f32 v121, v68, v69
	v_cvt_pk_bf16_f32 v122, v70, v71
	v_cvt_pk_bf16_f32 v123, v72, v73
	v_cvt_pk_bf16_f32 v116, v74, v75
	v_cvt_pk_bf16_f32 v117, v76, v77
	v_cvt_pk_bf16_f32 v118, v78, v79
	v_cvt_pk_bf16_f32 v119, v80, v81
	v_subrev_u32_e32 v142, 64, v142
	v_lshl_add_u64 v[132:133], v[132:133], 0, s[40:41]
	v_lshl_add_u64 v[134:135], v[134:135], 0, s[40:41]
	v_lshl_add_u64 v[136:137], v[136:137], 0, s[40:41]
	s_cmp_eq_u32 s74, s23
	v_lshl_add_u64 v[138:139], v[138:139], 0, s[40:41]
	s_cbranch_scc1 .LBB0_643
	s_mov_b32 s18, s76
	s_branch .LBB0_633

; #define MFMA16(a, b, c) __builtin_amdgcn_mfma_f32_16x16x32_bf16((a), (b), (c), 0, 0, 0)
; __device__ __forceinline__ bf16x8 cvt8(f32x4 a, f32x4 b) { v4u w = {pk2(a[0], a[1]), pk2(a[2], a[3]), pk2(b[0], b[1]), pk2(b[2], b[3])}; return __builtin_bit_cast(bf16x8, w); }
; #define DEC_LOADV(VB_, NEW_) do { _Pragma("unroll") for (int j = 0; j < 8; ++j) { int key_ = (j < 4) ? vkey0 + j : 16 + vkey0 + (j - 4); if (NEW_) key_ = key_ > 3 ? 3 : key_; \
;         _Pragma("unroll") for (int hf = 0; hf < 2; ++hf) vr[j][hf] = *(const f32x4*)((VB_) + (size_t)key_ * 512 + 64 * hf + 4 * n); } } while (0)
; __device__ __forceinline__ void decode_unit(int item, const float* ck, const float* cv, const int* pt, const bf16* QB, const float* ksamp, const float* vsamp, bf16* MIX_unused_, LAS unsigned char* lds, const LAS float* BL, float lam, float* PART, gu32* dcnt, bf16* MIX, gu32* rdy4) {
;     ...
;     for (int i = 0; i < NIT; ++i) {
;         __builtin_amdgcn_sched_barrier(0);
;         DEC_LOADV(vbase, isnew);
;         __builtin_amdgcn_sched_barrier(0);
;         f32x4 s[2];
; #pragma unroll
;         for (int sub = 0; sub < 2; ++sub) {
;             s[sub] = (f32x4){0.f, 0.f, 0.f, 0.f};
; #pragma unroll
;             for (int mp = 0; mp < 2; ++mp)
; #pragma unroll
;                 for (int ks = 0; ks < 2; ++ks) s[sub] = MFMA16(cvt8(kr[sub][mp][ks][0], kr[sub][mp][ks][1]), qfl[(mp * 2 + ks) * 64], s[sub]);
;         }
;         const int key0c = key0; const bool isnewc = isnew;
;         __builtin_amdgcn_sched_barrier(0);
;         const float* vb_cur = vbase;
;         if (i + 1 < NIT) { DEC_BASES(i + 1, kbase, vbase, key0, isnew); DEC_LOADK(kbase, isnew); }
;         __builtin_amdgcn_sched_barrier(0);
.LBB0_665:
	s_sleep 32
	v_lshlrev_b32_e32 v98, 2, v194
	v_lshlrev_b32_e32 v98, 2, v98
	v_cndmask_b32_e64 v100, v223, v225, s[76:77]
	v_cndmask_b32_e64 v104, v226, v227, s[76:77]
	v_cndmask_b32_e64 v108, v228, v229, s[76:77]
	v_lshl_add_u64 v[132:133], s[78:79], 0, v[98:99]
	v_lshlrev_b32_e32 v100, 11, v100
	v_mov_b32_e32 v101, v99
	v_lshlrev_b32_e32 v104, 11, v104
	v_mov_b32_e32 v105, v99
	v_lshlrev_b32_e32 v108, 11, v108
	v_mov_b32_e32 v109, v99
	v_cndmask_b32_e64 v112, v198, v246, s[76:77]
	v_mov_b32_e32 v113, v99
	v_cndmask_b32_e64 v116, v200, v246, s[76:77]
	v_mov_b32_e32 v117, v99
	v_cndmask_b32_e64 v120, v202, v246, s[76:77]
	v_mov_b32_e32 v121, v99
	v_cndmask_b32_e64 v128, v204, v246, s[76:77]
	v_mov_b32_e32 v129, v99
	v_cndmask_b32_e64 v134, v206, v246, s[76:77]
	v_mov_b32_e32 v135, v99
	v_lshl_add_u64 v[100:101], v[132:133], 0, v[100:101]
	v_lshl_add_u64 v[104:105], v[132:133], 0, v[104:105]
	v_lshl_add_u64 v[108:109], v[132:133], 0, v[108:109]
	v_lshl_add_u64 v[112:113], v[132:133], 0, v[112:113]
	v_lshl_add_u64 v[116:117], v[132:133], 0, v[116:117]
	v_lshl_add_u64 v[120:121], v[132:133], 0, v[120:121]
	v_lshl_add_u64 v[128:129], v[132:133], 0, v[128:129]
	v_lshl_add_u64 v[132:133], v[132:133], 0, v[134:135]
	global_load_dwordx4 v[124:127], v[100:101], off
	s_nop 0
	global_load_dwordx4 v[100:103], v[100:101], off offset:256
	s_nop 0
	global_load_dwordx4 v[136:139], v[104:105], off
	s_nop 0
	global_load_dwordx4 v[104:107], v[104:105], off offset:256
	s_nop 0
	global_load_dwordx4 v[140:143], v[108:109], off
	s_nop 0
	global_load_dwordx4 v[108:111], v[108:109], off offset:256
	s_nop 0
	global_load_dwordx4 v[144:147], v[112:113], off
	s_nop 0
	global_load_dwordx4 v[112:115], v[112:113], off offset:256
	s_nop 0
	global_load_dwordx4 v[148:151], v[116:117], off
	s_nop 0
	global_load_dwordx4 v[116:119], v[116:117], off offset:256
	s_nop 0
	global_load_dwordx4 v[152:155], v[120:121], off
	s_nop 0
	global_load_dwordx4 v[120:123], v[120:121], off offset:256
	s_nop 0
	global_load_dwordx4 v[156:159], v[128:129], off
	s_nop 0
	global_load_dwordx4 v[128:131], v[128:129], off offset:256
	s_nop 0
	global_load_dwordx4 v[160:163], v[132:133], off
	s_nop 0
	global_load_dwordx4 v[132:135], v[132:133], off offset:256
	s_waitcnt vmcnt(30)
	v_cvt_pk_bf16_f32 v62, v62, v63
	v_cvt_pk_bf16_f32 v63, v64, v65
	v_cvt_pk_bf16_f32 v64, v58, v59
	v_cvt_pk_bf16_f32 v65, v60, v61
	ds_read_b128 v[58:61], v213 offset:40960
	s_waitcnt vmcnt(28)
	v_cvt_pk_bf16_f32 v54, v54, v55
	v_cvt_pk_bf16_f32 v55, v56, v57
	v_cvt_pk_bf16_f32 v56, v50, v51
	v_cvt_pk_bf16_f32 v57, v52, v53
	ds_read_b128 v[50:53], v213 offset:41984
	s_waitcnt lgkmcnt(1)
	v_mfma_f32_16x16x32_bf16 v[62:65], v[62:65], v[58:61], 0
	s_waitcnt vmcnt(26)
	v_cvt_pk_bf16_f32 v46, v46, v47
	v_cvt_pk_bf16_f32 v47, v48, v49
	v_cvt_pk_bf16_f32 v48, v42, v43
	v_cvt_pk_bf16_f32 v49, v44, v45
	ds_read_b128 v[42:45], v213 offset:43008
	s_waitcnt lgkmcnt(1)
	v_mfma_f32_16x16x32_bf16 v[54:57], v[54:57], v[50:53], v[62:65]
	s_waitcnt vmcnt(24)
	v_cvt_pk_bf16_f32 v38, v38, v39
	v_cvt_pk_bf16_f32 v39, v40, v41
	v_cvt_pk_bf16_f32 v40, v34, v35
	v_cvt_pk_bf16_f32 v41, v36, v37
	ds_read_b128 v[34:37], v213 offset:44032
	s_waitcnt lgkmcnt(1)
	v_mfma_f32_16x16x32_bf16 v[46:49], v[46:49], v[42:45], v[54:57]
	s_waitcnt lgkmcnt(0)
	v_mfma_f32_16x16x32_bf16 v[164:167], v[38:41], v[34:37], v[46:49]
	s_waitcnt vmcnt(22)
	v_cvt_pk_bf16_f32 v38, v94, v95
	v_cvt_pk_bf16_f32 v39, v96, v97
	s_waitcnt vmcnt(22)
	v_cvt_pk_bf16_f32 v40, v86, v87
	v_cvt_pk_bf16_f32 v41, v88, v89
	s_waitcnt vmcnt(20)
	v_cvt_pk_bf16_f32 v46, v90, v91
	v_cvt_pk_bf16_f32 v47, v92, v93
	s_waitcnt vmcnt(19)
	v_cvt_pk_bf16_f32 v48, v82, v83
	v_cvt_pk_bf16_f32 v49, v84, v85
	v_mfma_f32_16x16x32_bf16 v[38:41], v[38:41], v[58:61], 0
	s_nop 0
	v_mfma_f32_16x16x32_bf16 v[38:41], v[46:49], v[50:53], v[38:41]
	s_waitcnt vmcnt(18)
	v_cvt_pk_bf16_f32 v46, v70, v71
	v_cvt_pk_bf16_f32 v47, v72, v73
	s_waitcnt vmcnt(17)
	v_cvt_pk_bf16_f32 v48, v78, v79
	v_cvt_pk_bf16_f32 v49, v80, v81
	s_nop 1
	v_mfma_f32_16x16x32_bf16 v[38:41], v[46:49], v[42:45], v[38:41]
	s_waitcnt vmcnt(16)
	v_cvt_pk_bf16_f32 v42, v66, v67
	v_cvt_pk_bf16_f32 v43, v68, v69
	s_waitcnt vmcnt(16)
	v_cvt_pk_bf16_f32 v44, v74, v75
	v_cvt_pk_bf16_f32 v45, v76, v77
	s_nop 1
	v_mfma_f32_16x16x32_bf16 v[168:171], v[42:45], v[34:37], v[38:41]
	s_cmpk_eq_i32 s91, 0x1c0
	s_cselect_b64 s[74:75], -1, 0
	s_and_b64 vcc, exec, s[74:75]
	s_cbranch_vccnz .LBB0_667
	s_lshr_b32 s78, s94, 2
	v_readlane_b32 s78, v217, s78
	s_ashr_i32 s79, s78, 31
	s_and_b32 s80, s95, 0xc000
	s_lshl_b64 s[78:79], s[78:79], 16
	s_or_b32 s78, s78, s80
	s_or_b64 s[78:79], s[78:79], s[28:29]
	s_lshl_b64 s[78:79], s[78:79], 2
	s_add_u32 s80, s20, s78
	s_addc_u32 s81, s21, s79
	s_add_u32 s78, s22, s78
	s_addc_u32 s79, s23, s79
	s_add_i32 s96, s93, s91
	v_mov_b32_e32 v34, v232
	v_mov_b64_e32 v[66:67], v[208:209]
	s_branch .LBB0_668

; #define PG8_LAS __attribute__((address_space(3)))
;     __device__ __forceinline__ void operator()(const f32x4 (&acc)[2][2][4][2], const Unit& u, int wr, int wc, int fr, int fq) const {
;     ...
;             for (int n = 0; n < 2; ++n) {
;                 const f32x4 w0 = *(const f32x4*)(cw + colt + 4 * n), w1 = *(const f32x4*)(cw + 2816 + colt + 4 * n), w2 = *(const f32x4*)(cw + 5632 + colt + 4 * n), bb = *(const f32x4*)(cb + colt + 4 * n);
; #pragma unroll
;                 for (int ai = 0; ai < 2; ++ai) {
;                     f32x4 prevA = {0.f, 0.f, 0.f, 0.f};
;                     const bool has_prev = (wr == 1) || (ai == 1);
;     ...
;                     if (has_prev && fr >= 14) { const int pw = (wr == 1 ? 0 : 4) + wc, pai = (wr == 1) ? ai : 0; prevA = *(const PG8_LAS f32x4*)(xch + ((pw * 8 + (fr - 14) * 4 + fq) * 16 + pai * 8 + n * 4)); }
;     ...
; #pragma unroll
;                     for (int m = 0; m < 4; ++m) {
;                         const int row = row0 + ai * HALF + m * 16;
;                         const f32x4 a = acc[ai][0][m][n] * rs[ai][m], uu = acc[ai][1][m][n] * rs[ai][m]; f32x4 gg;
; #pragma unroll
;                         for (int j = 0; j < 4; ++j) {
;                             const float p1 = __builtin_bit_cast(float, __builtin_amdgcn_ds_bpermute(idx1, __builtin_bit_cast(int, fr == 15 ? prevA[j] : a[j])));
;                             const float p2 = __builtin_bit_cast(float, __builtin_amdgcn_ds_bpermute(idx2, __builtin_bit_cast(int, fr >= 14 ? prevA[j] : a[j])));
;                             const float c = bb[j] + w0[j] * p2 + w1[j] * p1 + w2[j] * a[j];
;                             gg[j] = c * sigm(c) * uu[j];
;                         }
;                         *(u32x2*)(G + (size_t)row * 2816 + colt + 4 * n) = (u32x2){cvt_pk_bf16(gg[0], gg[1]), cvt_pk_bf16(gg[2], gg[3])};
;                         if (ai == 0 && m == 0 && wr == 0 && fr < 2) { *(f32x4*)(HALO_A + (size_t)(u.pm * 2 + fr) * 2816 + colt + 4 * n) = a; *(f32x4*)(HALO_U + (size_t)(u.pm * 2 + fr) * 2816 + colt + 4 * n) = uu; }
;                         if (ai == 1 && m == 3 && wr == 1 && fr >= 14) { *(f32x4*)(LASTA + (size_t)(u.pm * 2 + fr - 14) * 2816 + colt + 4 * n) = a;
;                             if ((u.pm & 31) == 31) *(f32x4*)(ocp + (size_t)((u.pm >> 5) * 2 + fr - 14) * 2816 + colt + 4 * n) = a; }
.LBB0_998:
	s_or_b64 exec, exec, s[8:9]
	s_waitcnt lgkmcnt(0)
	s_barrier
	s_load_dwordx4 s[20:23], s[14:15], 0x98
	v_lshlrev_b64 v[194:195], 2, v[168:169]
	v_lshl_add_u64 v[134:135], s[72:73], 0, v[194:195]
	v_lshl_add_u64 v[138:139], s[74:75], 0, v[194:195]
	v_readlane_b32 s8, v255, 25
	s_waitcnt lgkmcnt(0)
	v_lshl_add_u64 v[196:197], s[20:21], 0, v[194:195]
	v_lshl_add_u64 v[198:199], s[22:23], 0, v[194:195]
	global_load_dwordx4 v[130:133], v[196:197], off
	s_nop 0
	global_load_dwordx4 v[134:137], v[134:135], off
	s_nop 0
	global_load_dwordx4 v[138:141], v[138:139], off
	v_lshlrev_b32_e32 v171, 6, v239
	global_load_dwordx4 v[142:145], v[198:199], off
	v_add_co_u32_e32 v248, vcc, 0x2000, v196
	global_load_dwordx4 v[218:221], v[196:197], off offset:16
	s_nop 0
	v_addc_co_u32_e32 v249, vcc, 0, v197, vcc
	v_add_co_u32_e32 v250, vcc, 0x5000, v196
	s_nop 1
	v_addc_co_u32_e32 v251, vcc, 0, v197, vcc
	global_load_dwordx4 v[222:225], v[248:249], off offset:3088
	global_load_dwordx4 v[226:229], v[250:251], off offset:2064
	global_load_dwordx4 v[244:247], v[198:199], off offset:16
	s_and_b64 s[12:13], s[40:41], s[6:7]
	v_mov_b32_e32 v154, 0
	v_add_u32_e32 v173, s8, v146
	v_mov_b32_e32 v155, 0
	v_mov_b32_e32 v156, 0
	v_mov_b32_e32 v157, 0
	s_and_saveexec_b64 s[8:9], s[12:13]
	s_movk_i32 s20, 0xf200
	v_add3_u32 v146, v173, v171, s20
	ds_read_b128 v[154:157], v146
	s_or_b64 exec, exec, s[8:9]
	v_cmp_eq_u32_e32 vcc, 0, v237
	v_cmp_eq_u32_e64 s[8:9], 15, v237
	v_pk_mul_f32 v[148:149], v[128:129], v[184:185] op_sel_hi:[1,0]
	v_cndmask_b32_e64 v146, -1, 15, vcc
	v_cmp_gt_u32_e32 vcc, 2, v237
	v_add_lshl_u32 v209, v146, v238, 2
	v_pk_mul_f32 v[152:153], v[96:97], v[184:185] op_sel_hi:[1,0]
	v_cndmask_b32_e64 v146, -2, 14, vcc
	v_add_lshl_u32 v208, v146, v238, 2
	v_pk_mul_f32 v[146:147], v[126:127], v[184:185] op_sel_hi:[1,0]
	v_pk_mul_f32 v[150:151], v[94:95], v[184:185] op_sel_hi:[1,0]
	s_waitcnt lgkmcnt(0)
	v_cndmask_b32_e64 v175, v146, v154, s[8:9]
	ds_bpermute_b32 v200, v209, v175
	v_cndmask_b32_e64 v154, v146, v154, s[6:7]
	v_cndmask_b32_e64 v175, v147, v155, s[8:9]
	v_cndmask_b32_e64 v155, v147, v155, s[6:7]
	ds_bpermute_b32 v154, v208, v154
	ds_bpermute_b32 v155, v208, v155
	ds_bpermute_b32 v201, v209, v175
	s_and_b64 s[88:89], s[70:71], vcc
	s_waitcnt vmcnt(0) lgkmcnt(1)
	v_pk_fma_f32 v[154:155], v[130:131], v[154:155], v[142:143]
	s_waitcnt lgkmcnt(0)
	v_pk_fma_f32 v[154:155], v[134:135], v[200:201], v[154:155]
	s_nop 0
	v_pk_fma_f32 v[154:155], v[146:147], v[138:139], v[154:155]
	s_nop 0
	v_mul_f32_e32 v175, 0xbfb8aa3b, v154
	v_exp_f32_e32 v175, v175
	s_nop 0
	v_add_f32_e32 v175, 1.0, v175
	v_rcp_f32_e32 v200, v175
	v_mul_f32_e32 v175, 0xbfb8aa3b, v155
	v_exp_f32_e32 v175, v175
	s_nop 0
	v_add_f32_e32 v175, 1.0, v175
	v_rcp_f32_e32 v201, v175
	v_cndmask_b32_e64 v175, v148, v156, s[8:9]
	v_cndmask_b32_e64 v156, v148, v156, s[6:7]
	ds_bpermute_b32 v156, v208, v156
	v_pk_mul_f32 v[154:155], v[154:155], v[200:201]
	ds_bpermute_b32 v200, v209, v175
	v_cndmask_b32_e64 v175, v149, v157, s[8:9]
	v_cndmask_b32_e64 v157, v149, v157, s[6:7]
	ds_bpermute_b32 v157, v208, v157
	ds_bpermute_b32 v201, v209, v175
	v_pk_mul_f32 v[154:155], v[150:151], v[154:155]
	s_waitcnt lgkmcnt(1)
	v_pk_fma_f32 v[156:157], v[132:133], v[156:157], v[144:145]
	s_waitcnt lgkmcnt(0)
	v_pk_fma_f32 v[156:157], v[136:137], v[200:201], v[156:157]
	v_cvt_pk_bf16_f32 v154, v154, v155
	v_pk_fma_f32 v[156:157], v[148:149], v[140:141], v[156:157]
	s_nop 0
	v_mul_f32_e32 v175, 0xbfb8aa3b, v156
	v_exp_f32_e32 v175, v175
	s_nop 0
	v_add_f32_e32 v175, 1.0, v175
	v_rcp_f32_e32 v200, v175
	v_mul_f32_e32 v175, 0xbfb8aa3b, v157
	v_exp_f32_e32 v175, v175
	s_nop 0
	v_add_f32_e32 v175, 1.0, v175
	v_rcp_f32_e32 v201, v175
	v_lshl_or_b32 v175, s34, 1, v237
	v_pk_mul_f32 v[156:157], v[156:157], v[200:201]
	s_nop 0
	v_pk_mul_f32 v[156:157], v[152:153], v[156:157]
	s_nop 0
	v_cvt_pk_bf16_f32 v155, v156, v157
	v_mov_b64_e32 v[156:157], s[42:43]
	v_mad_i64_i32 v[156:157], s[20:21], v192, s47, v[156:157]
	v_lshl_add_u64 v[206:207], v[168:169], 1, v[156:157]
	global_store_dwordx2 v[206:207], v[154:155], off
	s_and_saveexec_b64 s[90:91], s[88:89]
	s_cbranch_execz .LBB0_1002
	v_readlane_b32 s20, v255, 16
	v_readlane_b32 s21, v255, 17
	s_nop 1
	v_mov_b64_e32 v[154:155], s[20:21]
	v_mad_i64_i32 v[154:155], s[20:21], v175, s48, v[154:155]
	v_readlane_b32 s20, v255, 18
	v_lshl_add_u64 v[154:155], v[154:155], 0, v[194:195]
	v_readlane_b32 s21, v255, 19
	global_store_dwordx4 v[154:155], v[146:149], off
	s_nop 0
	v_mov_b64_e32 v[154:155], s[20:21]
	v_mad_i64_i32 v[154:155], s[20:21], v175, s48, v[154:155]
	v_lshl_add_u64 v[154:155], v[154:155], 0, v[194:195]
	global_store_dwordx4 v[154:155], v[150:153], off

; #define PG8_LAS __attribute__((address_space(3)))
;     __device__ __forceinline__ void operator()(const f32x4 (&acc)[2][2][4][2], const Unit& u, int wr, int wc, int fr, int fq) const {
;     ...
;             for (int n = 0; n < 2; ++n) {
;                 const f32x4 w0 = *(const f32x4*)(cw + colt + 4 * n), w1 = *(const f32x4*)(cw + 2816 + colt + 4 * n), w2 = *(const f32x4*)(cw + 5632 + colt + 4 * n), bb = *(const f32x4*)(cb + colt + 4 * n);
; #pragma unroll
;                 for (int ai = 0; ai < 2; ++ai) {
;                     f32x4 prevA = {0.f, 0.f, 0.f, 0.f};
;                     const bool has_prev = (wr == 1) || (ai == 1);
;     ...
;                     if (has_prev && fr >= 14) { const int pw = (wr == 1 ? 0 : 4) + wc, pai = (wr == 1) ? ai : 0; prevA = *(const PG8_LAS f32x4*)(xch + ((pw * 8 + (fr - 14) * 4 + fq) * 16 + pai * 8 + n * 4)); }
;     ...
; #pragma unroll
;                     for (int m = 0; m < 4; ++m) {
;                         const int row = row0 + ai * HALF + m * 16;
;                         const f32x4 a = acc[ai][0][m][n] * rs[ai][m], uu = acc[ai][1][m][n] * rs[ai][m]; f32x4 gg;
; #pragma unroll
;                         for (int j = 0; j < 4; ++j) {
;                             const float p1 = __builtin_bit_cast(float, __builtin_amdgcn_ds_bpermute(idx1, __builtin_bit_cast(int, fr == 15 ? prevA[j] : a[j])));
;                             const float p2 = __builtin_bit_cast(float, __builtin_amdgcn_ds_bpermute(idx2, __builtin_bit_cast(int, fr >= 14 ? prevA[j] : a[j])));
;                             const float c = bb[j] + w0[j] * p2 + w1[j] * p1 + w2[j] * a[j];
;                             gg[j] = c * sigm(c) * uu[j];
;                         }
;                         *(u32x2*)(G + (size_t)row * 2816 + colt + 4 * n) = (u32x2){cvt_pk_bf16(gg[0], gg[1]), cvt_pk_bf16(gg[2], gg[3])};
;                         if (ai == 0 && m == 0 && wr == 0 && fr < 2) { *(f32x4*)(HALO_A + (size_t)(u.pm * 2 + fr) * 2816 + colt + 4 * n) = a; *(f32x4*)(HALO_U + (size_t)(u.pm * 2 + fr) * 2816 + colt + 4 * n) = uu; }
;                         if (ai == 1 && m == 3 && wr == 1 && fr >= 14) { *(f32x4*)(LASTA + (size_t)(u.pm * 2 + fr - 14) * 2816 + colt + 4 * n) = a;
;                             if ((u.pm & 31) == 31) *(f32x4*)(ocp + (size_t)((u.pm >> 5) * 2 + fr - 14) * 2816 + colt + 4 * n) = a; }
.LBB0_1007:
	s_or_b64 exec, exec, s[90:91]
	v_mov_b32_e32 v154, 0
	v_mov_b32_e32 v155, 0
	v_mov_b32_e32 v156, 0
	v_mov_b32_e32 v157, 0
	s_and_saveexec_b64 s[90:91], s[12:13]
	s_movk_i32 s20, 0xf210
	v_add3_u32 v146, v173, v171, s20
	ds_read_b128 v[154:157], v146
	s_or_b64 exec, exec, s[90:91]
	v_mov_b32_e32 v185, v184
	v_pk_mul_f32 v[146:147], v[122:123], v[184:185]
	v_mov_b32_e32 v150, v184
	v_mov_b32_e32 v151, v184
	s_waitcnt lgkmcnt(0)
	v_cndmask_b32_e64 v177, v146, v154, s[8:9]
	v_pk_mul_f32 v[148:149], v[124:125], v[150:151]
	v_pk_mul_f32 v[152:153], v[92:93], v[150:151]
	v_pk_mul_f32 v[150:151], v[90:91], v[184:185]
	ds_bpermute_b32 v184, v209, v177
	v_cndmask_b32_e64 v154, v146, v154, s[6:7]
	v_cndmask_b32_e64 v177, v147, v155, s[8:9]
	v_cndmask_b32_e64 v155, v147, v155, s[6:7]
	ds_bpermute_b32 v154, v208, v154
	ds_bpermute_b32 v155, v208, v155
	ds_bpermute_b32 v185, v209, v177
	s_waitcnt lgkmcnt(1)
	v_pk_fma_f32 v[154:155], v[218:219], v[154:155], v[244:245]
	s_waitcnt lgkmcnt(0)
	v_pk_fma_f32 v[154:155], v[222:223], v[184:185], v[154:155]
	s_nop 0
	v_pk_fma_f32 v[154:155], v[146:147], v[226:227], v[154:155]
	s_nop 0
	v_mul_f32_e32 v177, 0xbfb8aa3b, v154
	v_exp_f32_e32 v177, v177
	s_nop 0
	v_add_f32_e32 v177, 1.0, v177
	v_rcp_f32_e32 v184, v177
	v_mul_f32_e32 v177, 0xbfb8aa3b, v155
	v_exp_f32_e32 v177, v177
	s_nop 0
	v_add_f32_e32 v177, 1.0, v177
	v_rcp_f32_e32 v185, v177
	v_cndmask_b32_e64 v177, v148, v156, s[8:9]
	v_cndmask_b32_e64 v156, v148, v156, s[6:7]
	ds_bpermute_b32 v156, v208, v156
	v_pk_mul_f32 v[154:155], v[154:155], v[184:185]
	ds_bpermute_b32 v184, v209, v177
	v_cndmask_b32_e64 v177, v149, v157, s[8:9]
	v_cndmask_b32_e64 v157, v149, v157, s[6:7]
	ds_bpermute_b32 v157, v208, v157
	ds_bpermute_b32 v185, v209, v177
	v_pk_mul_f32 v[154:155], v[150:151], v[154:155]
	s_waitcnt lgkmcnt(1)
	v_pk_fma_f32 v[156:157], v[220:221], v[156:157], v[246:247]
	s_waitcnt lgkmcnt(0)
	v_pk_fma_f32 v[156:157], v[224:225], v[184:185], v[156:157]
	v_cvt_pk_bf16_f32 v154, v154, v155
	v_pk_fma_f32 v[156:157], v[148:149], v[228:229], v[156:157]
	s_nop 0
	v_mul_f32_e32 v177, 0xbfb8aa3b, v156
	v_exp_f32_e32 v177, v177
	s_nop 0
	v_add_f32_e32 v177, 1.0, v177
	v_rcp_f32_e32 v184, v177
	v_mul_f32_e32 v177, 0xbfb8aa3b, v157
	v_exp_f32_e32 v177, v177
	s_nop 0
	v_add_f32_e32 v177, 1.0, v177
	v_rcp_f32_e32 v185, v177
	s_nop 0
	v_pk_mul_f32 v[156:157], v[156:157], v[184:185]
	s_nop 0
	v_pk_mul_f32 v[156:157], v[152:153], v[156:157]
	s_nop 0
	v_cvt_pk_bf16_f32 v155, v156, v157
	global_store_dwordx2 v[206:207], v[154:155], off offset:8
	s_and_saveexec_b64 s[90:91], s[88:89]
	s_cbranch_execz .LBB0_1011
	v_readlane_b32 s20, v255, 16
	v_readlane_b32 s21, v255, 17
	s_nop 1
	v_mov_b64_e32 v[154:155], s[20:21]
	v_mad_i64_i32 v[154:155], s[20:21], v175, s48, v[154:155]
	v_readlane_b32 s20, v255, 18
	v_lshl_add_u64 v[154:155], v[154:155], 0, v[194:195]
	v_readlane_b32 s21, v255, 19
	global_store_dwordx4 v[154:155], v[146:149], off offset:16
	s_nop 0
	v_mov_b64_e32 v[154:155], s[20:21]
	v_mad_i64_i32 v[154:155], s[20:21], v175, s48, v[154:155]
	v_lshl_add_u64 v[154:155], v[154:155], 0, v[194:195]
	global_store_dwordx4 v[154:155], v[150:153], off offset:16
.LBB0_1011:
	s_or_b64 exec, exec, s[90:91]
	v_mov_b32_e32 v183, v182
	v_pk_mul_f32 v[154:155], v[114:115], v[182:183]
	v_mov_b32_e32 v152, v182
	v_cndmask_b32_e64 v175, v154, v146, s[8:9]
	v_mov_b32_e32 v153, v182
	v_pk_mul_f32 v[156:157], v[82:83], v[182:183]
	ds_bpermute_b32 v182, v209, v175
	v_cndmask_b32_e64 v146, v154, v146, s[6:7]
	v_cndmask_b32_e64 v175, v155, v147, s[8:9]
	v_cndmask_b32_e64 v147, v155, v147, s[6:7]
	ds_bpermute_b32 v146, v208, v146
	ds_bpermute_b32 v147, v208, v147
	ds_bpermute_b32 v183, v209, v175
	v_pk_mul_f32 v[150:151], v[116:117], v[152:153]
	v_mov_b32_e32 v181, v180
	v_pk_mul_f32 v[152:153], v[84:85], v[152:153]
	s_waitcnt lgkmcnt(1)
	v_pk_fma_f32 v[146:147], v[218:219], v[146:147], v[244:245]
	v_mov_b32_e32 v179, v178
	s_waitcnt lgkmcnt(0)
	v_pk_fma_f32 v[146:147], v[222:223], v[182:183], v[146:147]
	s_nop 0
	v_pk_fma_f32 v[146:147], v[154:155], v[226:227], v[146:147]
	s_nop 0
	v_mul_f32_e32 v175, 0xbfb8aa3b, v146
	v_exp_f32_e32 v175, v175
	s_nop 0
	v_add_f32_e32 v175, 1.0, v175
	v_rcp_f32_e32 v182, v175
	v_mul_f32_e32 v175, 0xbfb8aa3b, v147
	v_exp_f32_e32 v175, v175
	s_nop 0
	v_add_f32_e32 v175, 1.0, v175
	v_rcp_f32_e32 v183, v175
	s_nop 0
	v_pk_mul_f32 v[146:147], v[146:147], v[182:183]
	s_nop 0
	v_pk_mul_f32 v[146:147], v[156:157], v[146:147]
	v_cndmask_b32_e64 v156, v150, v148, s[8:9]
	v_cndmask_b32_e64 v148, v150, v148, s[6:7]
	v_cndmask_b32_e64 v157, v151, v149, s[8:9]
	v_cndmask_b32_e64 v149, v151, v149, s[6:7]
	ds_bpermute_b32 v148, v208, v148
	ds_bpermute_b32 v149, v208, v149
	ds_bpermute_b32 v156, v209, v156
	ds_bpermute_b32 v157, v209, v157
	v_cvt_pk_bf16_f32 v146, v146, v147
	s_waitcnt lgkmcnt(2)
	v_pk_fma_f32 v[148:149], v[220:221], v[148:149], v[246:247]
	s_waitcnt lgkmcnt(0)
	v_pk_fma_f32 v[148:149], v[224:225], v[156:157], v[148:149]
	s_nop 0
	v_pk_fma_f32 v[148:149], v[150:151], v[228:229], v[148:149]
	s_nop 0
	v_mul_f32_e32 v156, 0xbfb8aa3b, v148
	v_mul_f32_e32 v157, 0xbfb8aa3b, v149
	v_exp_f32_e32 v156, v156
	v_exp_f32_e32 v157, v157
	v_add_f32_e32 v156, 1.0, v156
	v_add_f32_e32 v157, 1.0, v157
	v_rcp_f32_e32 v156, v156
	v_rcp_f32_e32 v157, v157
	s_nop 0
	v_pk_mul_f32 v[148:149], v[148:149], v[156:157]
	s_nop 0
	v_pk_mul_f32 v[148:149], v[152:153], v[148:149]
	v_pk_mul_f32 v[152:153], v[106:107], v[180:181]
	v_cvt_pk_bf16_f32 v147, v148, v149
	v_cndmask_b32_e64 v175, v152, v154, s[8:9]
	v_mov_b32_e32 v148, v180
	v_mov_b32_e32 v149, v180
	v_pk_mul_f32 v[156:157], v[74:75], v[180:181]
	ds_bpermute_b32 v180, v209, v175
	v_cndmask_b32_e64 v154, v152, v154, s[6:7]
	v_cndmask_b32_e64 v175, v153, v155, s[8:9]
	v_cndmask_b32_e64 v155, v153, v155, s[6:7]
	ds_bpermute_b32 v154, v208, v154
	ds_bpermute_b32 v155, v208, v155
	ds_bpermute_b32 v181, v209, v175
	global_store_dwordx2 v[200:201], v[146:147], off offset:8
	v_pk_mul_f32 v[146:147], v[108:109], v[148:149]
	v_pk_mul_f32 v[148:149], v[76:77], v[148:149]
	s_waitcnt lgkmcnt(1)
; __device__ __forceinline__ unsigned cvt_pk_bf16(float lo, float hi) { f32x2_t v = {lo, hi}; bf16x2_t b = __builtin_convertvector(v, bf16x2_t); return __builtin_bit_cast(unsigned, b); }
; __device__ __forceinline__ float sigm(float x) { return __builtin_amdgcn_rcpf(1.0f + __builtin_amdgcn_exp2f(-x * LOG2E)); }
;     __device__ __forceinline__ void operator()(const f32x4 (&acc)[2][2][4][2], const Unit& u, int wr, int wc, int fr, int fq) const {
;     ...
; #pragma unroll
;                     for (int m = 0; m < 4; ++m) {
;                         const int row = row0 + ai * HALF + m * 16;
;                         const f32x4 a = acc[ai][0][m][n] * rs[ai][m], uu = acc[ai][1][m][n] * rs[ai][m]; f32x4 gg;
; #pragma unroll
;                         for (int j = 0; j < 4; ++j) {
;                             const float p1 = __builtin_bit_cast(float, __builtin_amdgcn_ds_bpermute(idx1, __builtin_bit_cast(int, fr == 15 ? prevA[j] : a[j])));
;                             const float p2 = __builtin_bit_cast(float, __builtin_amdgcn_ds_bpermute(idx2, __builtin_bit_cast(int, fr >= 14 ? prevA[j] : a[j])));
;                             const float c = bb[j] + w0[j] * p2 + w1[j] * p1 + w2[j] * a[j];
;                             gg[j] = c * sigm(c) * uu[j];
;                         }
;                         *(u32x2*)(G + (size_t)row * 2816 + colt + 4 * n) = (u32x2){cvt_pk_bf16(gg[0], gg[1]), cvt_pk_bf16(gg[2], gg[3])};
	v_pk_fma_f32 v[154:155], v[218:219], v[154:155], v[244:245]
	s_waitcnt lgkmcnt(0)
	v_pk_fma_f32 v[154:155], v[222:223], v[180:181], v[154:155]
	s_nop 0
	v_pk_fma_f32 v[154:155], v[152:153], v[226:227], v[154:155]
	s_nop 0
	v_mul_f32_e32 v175, 0xbfb8aa3b, v154
	v_exp_f32_e32 v175, v175
	s_nop 0
	v_add_f32_e32 v175, 1.0, v175
	v_rcp_f32_e32 v180, v175
	v_mul_f32_e32 v175, 0xbfb8aa3b, v155
	v_exp_f32_e32 v175, v175
	s_nop 0
	v_add_f32_e32 v175, 1.0, v175
	v_rcp_f32_e32 v181, v175
	s_nop 0
	v_pk_mul_f32 v[154:155], v[154:155], v[180:181]
	s_nop 0
	v_pk_mul_f32 v[154:155], v[156:157], v[154:155]
	v_cndmask_b32_e64 v156, v146, v150, s[8:9]
	v_cndmask_b32_e64 v150, v146, v150, s[6:7]
	v_cndmask_b32_e64 v157, v147, v151, s[8:9]
	v_cndmask_b32_e64 v151, v147, v151, s[6:7]
	ds_bpermute_b32 v150, v208, v150
	ds_bpermute_b32 v151, v208, v151
	ds_bpermute_b32 v156, v209, v156
	ds_bpermute_b32 v157, v209, v157
	s_waitcnt lgkmcnt(2)
	v_pk_fma_f32 v[150:151], v[220:221], v[150:151], v[246:247]
	s_waitcnt lgkmcnt(0)
	v_pk_fma_f32 v[150:151], v[224:225], v[156:157], v[150:151]
	s_nop 0
	v_pk_fma_f32 v[150:151], v[146:147], v[228:229], v[150:151]
	s_nop 0
	v_mul_f32_e32 v156, 0xbfb8aa3b, v150
	v_mul_f32_e32 v157, 0xbfb8aa3b, v151
	v_exp_f32_e32 v156, v156
	v_exp_f32_e32 v157, v157
	v_add_f32_e32 v156, 1.0, v156
	v_add_f32_e32 v157, 1.0, v157
	v_rcp_f32_e32 v156, v156
	v_rcp_f32_e32 v157, v157
	s_nop 0
	v_pk_mul_f32 v[150:151], v[150:151], v[156:157]
	s_nop 0
	v_pk_mul_f32 v[148:149], v[148:149], v[150:151]
	v_cvt_pk_bf16_f32 v150, v154, v155
	v_pk_mul_f32 v[154:155], v[98:99], v[178:179]
	v_cvt_pk_bf16_f32 v151, v148, v149
	v_cndmask_b32_e64 v175, v154, v152, s[8:9]
	v_mov_b32_e32 v148, v178
	v_mov_b32_e32 v149, v178
	v_pk_mul_f32 v[156:157], v[66:67], v[178:179]
	ds_bpermute_b32 v178, v209, v175
	v_cndmask_b32_e64 v152, v154, v152, s[6:7]
	v_cndmask_b32_e64 v175, v155, v153, s[8:9]
	v_cndmask_b32_e64 v153, v155, v153, s[6:7]
	ds_bpermute_b32 v152, v208, v152
	ds_bpermute_b32 v153, v208, v153
	ds_bpermute_b32 v179, v209, v175
	global_store_dwordx2 v[202:203], v[150:151], off offset:8
	v_pk_mul_f32 v[150:151], v[100:101], v[148:149]
	v_pk_mul_f32 v[148:149], v[68:69], v[148:149]
	s_waitcnt lgkmcnt(1)
	v_pk_fma_f32 v[152:153], v[218:219], v[152:153], v[244:245]
	s_waitcnt lgkmcnt(0)
	v_pk_fma_f32 v[152:153], v[222:223], v[178:179], v[152:153]
	s_nop 0
	v_pk_fma_f32 v[152:153], v[154:155], v[226:227], v[152:153]
	s_nop 0
	v_mul_f32_e32 v154, 0xbfb8aa3b, v152
	v_mul_f32_e32 v155, 0xbfb8aa3b, v153
	v_exp_f32_e32 v154, v154
	v_exp_f32_e32 v155, v155
	v_add_f32_e32 v154, 1.0, v154
	v_add_f32_e32 v155, 1.0, v155
	v_rcp_f32_e32 v154, v154
	v_rcp_f32_e32 v155, v155
	s_nop 0
	v_pk_mul_f32 v[152:153], v[152:153], v[154:155]
	v_cndmask_b32_e64 v154, v150, v146, s[8:9]
	v_cndmask_b32_e64 v146, v150, v146, s[6:7]
	v_cndmask_b32_e64 v155, v151, v147, s[8:9]
	v_cndmask_b32_e64 v147, v151, v147, s[6:7]
	ds_bpermute_b32 v146, v208, v146
	ds_bpermute_b32 v147, v208, v147
	ds_bpermute_b32 v154, v209, v154
	ds_bpermute_b32 v155, v209, v155
	v_pk_mul_f32 v[152:153], v[156:157], v[152:153]
	s_waitcnt lgkmcnt(2)
	v_pk_fma_f32 v[146:147], v[220:221], v[146:147], v[246:247]
	s_waitcnt lgkmcnt(0)
	v_pk_fma_f32 v[146:147], v[224:225], v[154:155], v[146:147]
	s_nop 0
	v_pk_fma_f32 v[146:147], v[150:151], v[228:229], v[146:147]
	s_nop 0
	v_mul_f32_e32 v150, 0xbfb8aa3b, v146
	v_mul_f32_e32 v151, 0xbfb8aa3b, v147
	v_exp_f32_e32 v150, v150
	v_exp_f32_e32 v151, v151
	v_add_f32_e32 v150, 1.0, v150
	v_add_f32_e32 v151, 1.0, v151
	v_rcp_f32_e32 v150, v150
	v_rcp_f32_e32 v151, v151
	s_nop 0
	v_pk_mul_f32 v[146:147], v[146:147], v[150:151]
	s_nop 0
	v_pk_mul_f32 v[146:147], v[148:149], v[146:147]
	v_cvt_pk_bf16_f32 v148, v152, v153
	v_cvt_pk_bf16_f32 v149, v146, v147
	global_store_dwordx2 v[204:205], v[148:149], off offset:8
	v_mov_b32_e32 v146, 0
	v_mov_b32_e32 v147, 0
	v_mov_b32_e32 v148, 0
	v_mov_b32_e32 v149, 0
	s_and_saveexec_b64 s[88:89], s[6:7]
	s_cbranch_execz .LBB0_1013
	v_readlane_b32 s20, v255, 15
	s_lshl_b32 s20, s20, 2
	s_nop 0
	v_add3_u32 v146, v173, v171, s20
	v_add_u32_e32 v146, 0xfffff210, v146
	ds_read_b128 v[146:149], v146
.LBB0_1013:
	s_or_b64 exec, exec, s[88:89]
	v_mov_b32_e32 v177, v176
	v_pk_mul_f32 v[154:155], v[58:59], v[176:177]
	v_mov_b32_e32 v152, v176
	v_mov_b32_e32 v153, v176
	v_pk_mul_f32 v[156:157], v[26:27], v[176:177]
	s_waitcnt lgkmcnt(0)
	v_cndmask_b32_e64 v176, v154, v146, s[8:9]
	v_cndmask_b32_e64 v146, v154, v146, s[6:7]
	v_cndmask_b32_e64 v177, v155, v147, s[8:9]
	v_cndmask_b32_e64 v147, v155, v147, s[6:7]
	ds_bpermute_b32 v146, v208, v146
	ds_bpermute_b32 v147, v208, v147
	ds_bpermute_b32 v176, v209, v176
	ds_bpermute_b32 v177, v209, v177
	v_pk_mul_f32 v[150:151], v[60:61], v[152:153]
	v_mov_b32_e32 v175, v174
	s_waitcnt lgkmcnt(2)
	v_pk_fma_f32 v[146:147], v[218:219], v[146:147], v[244:245]
	v_pk_mul_f32 v[152:153], v[28:29], v[152:153]
	s_waitcnt lgkmcnt(0)
	v_pk_fma_f32 v[146:147], v[222:223], v[176:177], v[146:147]
	v_mov_b32_e32 v173, v172
	v_pk_fma_f32 v[146:147], v[154:155], v[226:227], v[146:147]
	v_mov_b32_e32 v171, v170
	v_mul_f32_e32 v176, 0xbfb8aa3b, v146
	v_mul_f32_e32 v177, 0xbfb8aa3b, v147
	v_exp_f32_e32 v176, v176
	v_exp_f32_e32 v177, v177
	v_add_f32_e32 v176, 1.0, v176
	v_add_f32_e32 v177, 1.0, v177
	v_rcp_f32_e32 v176, v176
	v_rcp_f32_e32 v177, v177
	s_nop 0
	v_pk_mul_f32 v[146:147], v[146:147], v[176:177]
	s_nop 0
	v_pk_mul_f32 v[146:147], v[156:157], v[146:147]
	v_cndmask_b32_e64 v156, v150, v148, s[8:9]
	v_cndmask_b32_e64 v148, v150, v148, s[6:7]
	v_cndmask_b32_e64 v157, v151, v149, s[8:9]
	v_cndmask_b32_e64 v149, v151, v149, s[6:7]
	ds_bpermute_b32 v148, v208, v148
	ds_bpermute_b32 v149, v208, v149
	ds_bpermute_b32 v156, v209, v156
	ds_bpermute_b32 v157, v209, v157
	v_cvt_pk_bf16_f32 v146, v146, v147
	s_waitcnt lgkmcnt(2)
; __device__ __forceinline__ unsigned cvt_pk_bf16(float lo, float hi) { f32x2_t v = {lo, hi}; bf16x2_t b = __builtin_convertvector(v, bf16x2_t); return __builtin_bit_cast(unsigned, b); }
; __device__ __forceinline__ float sigm(float x) { return __builtin_amdgcn_rcpf(1.0f + __builtin_amdgcn_exp2f(-x * LOG2E)); }
;     __device__ __forceinline__ void operator()(const f32x4 (&acc)[2][2][4][2], const Unit& u, int wr, int wc, int fr, int fq) const {
;     ...
; #pragma unroll
;                     for (int m = 0; m < 4; ++m) {
;                         const int row = row0 + ai * HALF + m * 16;
;                         const f32x4 a = acc[ai][0][m][n] * rs[ai][m], uu = acc[ai][1][m][n] * rs[ai][m]; f32x4 gg;
; #pragma unroll
;                         for (int j = 0; j < 4; ++j) {
;                             const float p1 = __builtin_bit_cast(float, __builtin_amdgcn_ds_bpermute(idx1, __builtin_bit_cast(int, fr == 15 ? prevA[j] : a[j])));
;                             const float p2 = __builtin_bit_cast(float, __builtin_amdgcn_ds_bpermute(idx2, __builtin_bit_cast(int, fr >= 14 ? prevA[j] : a[j])));
;                             const float c = bb[j] + w0[j] * p2 + w1[j] * p1 + w2[j] * a[j];
;                             gg[j] = c * sigm(c) * uu[j];
;                         }
;                         *(u32x2*)(G + (size_t)row * 2816 + colt + 4 * n) = (u32x2){cvt_pk_bf16(gg[0], gg[1]), cvt_pk_bf16(gg[2], gg[3])};
	v_pk_fma_f32 v[148:149], v[220:221], v[148:149], v[246:247]
	s_waitcnt lgkmcnt(0)
	v_pk_fma_f32 v[148:149], v[224:225], v[156:157], v[148:149]
	s_nop 0
	v_pk_fma_f32 v[148:149], v[150:151], v[228:229], v[148:149]
	s_nop 0
	v_mul_f32_e32 v156, 0xbfb8aa3b, v148
	v_mul_f32_e32 v157, 0xbfb8aa3b, v149
	v_exp_f32_e32 v156, v156
	v_exp_f32_e32 v157, v157
	v_add_f32_e32 v156, 1.0, v156
	v_add_f32_e32 v157, 1.0, v157
	v_rcp_f32_e32 v156, v156
	v_rcp_f32_e32 v157, v157
	s_nop 0
	v_pk_mul_f32 v[148:149], v[148:149], v[156:157]
	s_nop 0
	v_pk_mul_f32 v[148:149], v[152:153], v[148:149]
	v_pk_mul_f32 v[152:153], v[50:51], v[174:175]
	v_cvt_pk_bf16_f32 v147, v148, v149
	v_mov_b32_e32 v148, v174
	v_mov_b32_e32 v149, v174
	v_pk_mul_f32 v[156:157], v[18:19], v[174:175]
	v_cndmask_b32_e64 v174, v152, v154, s[8:9]
	v_cndmask_b32_e64 v154, v152, v154, s[6:7]
	v_cndmask_b32_e64 v175, v153, v155, s[8:9]
	v_cndmask_b32_e64 v155, v153, v155, s[6:7]
	ds_bpermute_b32 v154, v208, v154
	ds_bpermute_b32 v155, v208, v155
	ds_bpermute_b32 v174, v209, v174
	ds_bpermute_b32 v175, v209, v175
	global_store_dwordx2 v[188:189], v[146:147], off offset:8
	v_pk_mul_f32 v[146:147], v[52:53], v[148:149]
	s_waitcnt lgkmcnt(2)
	v_pk_fma_f32 v[154:155], v[218:219], v[154:155], v[244:245]
	v_pk_mul_f32 v[148:149], v[20:21], v[148:149]
	s_waitcnt lgkmcnt(0)
	v_pk_fma_f32 v[154:155], v[222:223], v[174:175], v[154:155]
	s_nop 0
	v_pk_fma_f32 v[154:155], v[152:153], v[226:227], v[154:155]
	s_nop 0
	v_mul_f32_e32 v174, 0xbfb8aa3b, v154
	v_mul_f32_e32 v175, 0xbfb8aa3b, v155
	v_exp_f32_e32 v174, v174
	v_exp_f32_e32 v175, v175
	v_add_f32_e32 v174, 1.0, v174
	v_add_f32_e32 v175, 1.0, v175
	v_rcp_f32_e32 v174, v174
	v_rcp_f32_e32 v175, v175
	s_nop 0
	v_pk_mul_f32 v[154:155], v[154:155], v[174:175]
	s_nop 0
	v_pk_mul_f32 v[154:155], v[156:157], v[154:155]
	v_cndmask_b32_e64 v156, v146, v150, s[8:9]
	v_cndmask_b32_e64 v150, v146, v150, s[6:7]
	v_cndmask_b32_e64 v157, v147, v151, s[8:9]
	v_cndmask_b32_e64 v151, v147, v151, s[6:7]
	ds_bpermute_b32 v150, v208, v150
	ds_bpermute_b32 v151, v208, v151
	ds_bpermute_b32 v156, v209, v156
	ds_bpermute_b32 v157, v209, v157
	s_waitcnt lgkmcnt(2)
	v_pk_fma_f32 v[150:151], v[220:221], v[150:151], v[246:247]
	s_waitcnt lgkmcnt(0)
	v_pk_fma_f32 v[150:151], v[224:225], v[156:157], v[150:151]
	s_nop 0
	v_pk_fma_f32 v[150:151], v[146:147], v[228:229], v[150:151]
	s_nop 0
	v_mul_f32_e32 v156, 0xbfb8aa3b, v150
	v_mul_f32_e32 v157, 0xbfb8aa3b, v151
	v_exp_f32_e32 v156, v156
	v_exp_f32_e32 v157, v157
	v_add_f32_e32 v156, 1.0, v156
	v_add_f32_e32 v157, 1.0, v157
	v_rcp_f32_e32 v156, v156
	v_rcp_f32_e32 v157, v157
	s_nop 0
	v_pk_mul_f32 v[150:151], v[150:151], v[156:157]
	s_nop 0
	v_pk_mul_f32 v[148:149], v[148:149], v[150:151]
	v_cvt_pk_bf16_f32 v150, v154, v155
	v_pk_mul_f32 v[154:155], v[42:43], v[172:173]
	v_cvt_pk_bf16_f32 v151, v148, v149
	v_mov_b32_e32 v148, v172
	v_mov_b32_e32 v149, v172
	v_pk_mul_f32 v[156:157], v[10:11], v[172:173]
	v_cndmask_b32_e64 v172, v154, v152, s[8:9]
	v_cndmask_b32_e64 v152, v154, v152, s[6:7]
	v_cndmask_b32_e64 v173, v155, v153, s[8:9]
	v_cndmask_b32_e64 v153, v155, v153, s[6:7]
	ds_bpermute_b32 v152, v208, v152
	ds_bpermute_b32 v153, v208, v153
	ds_bpermute_b32 v172, v209, v172
	ds_bpermute_b32 v173, v209, v173
	global_store_dwordx2 v[190:191], v[150:151], off offset:8
	v_pk_mul_f32 v[150:151], v[44:45], v[148:149]
	s_waitcnt lgkmcnt(2)
	v_pk_fma_f32 v[152:153], v[218:219], v[152:153], v[244:245]
	v_pk_mul_f32 v[148:149], v[12:13], v[148:149]
	s_waitcnt lgkmcnt(0)
; __device__ __forceinline__ unsigned cvt_pk_bf16(float lo, float hi) { f32x2_t v = {lo, hi}; bf16x2_t b = __builtin_convertvector(v, bf16x2_t); return __builtin_bit_cast(unsigned, b); }
; __device__ __forceinline__ float sigm(float x) { return __builtin_amdgcn_rcpf(1.0f + __builtin_amdgcn_exp2f(-x * LOG2E)); }
;     __device__ __forceinline__ void operator()(const f32x4 (&acc)[2][2][4][2], const Unit& u, int wr, int wc, int fr, int fq) const {
;     ...
; #pragma unroll
;                     for (int m = 0; m < 4; ++m) {
;                         const int row = row0 + ai * HALF + m * 16;
;                         const f32x4 a = acc[ai][0][m][n] * rs[ai][m], uu = acc[ai][1][m][n] * rs[ai][m]; f32x4 gg;
; #pragma unroll
;                         for (int j = 0; j < 4; ++j) {
;                             const float p1 = __builtin_bit_cast(float, __builtin_amdgcn_ds_bpermute(idx1, __builtin_bit_cast(int, fr == 15 ? prevA[j] : a[j])));
;                             const float p2 = __builtin_bit_cast(float, __builtin_amdgcn_ds_bpermute(idx2, __builtin_bit_cast(int, fr >= 14 ? prevA[j] : a[j])));
;                             const float c = bb[j] + w0[j] * p2 + w1[j] * p1 + w2[j] * a[j];
;                             gg[j] = c * sigm(c) * uu[j];
;                         }
;                         *(u32x2*)(G + (size_t)row * 2816 + colt + 4 * n) = (u32x2){cvt_pk_bf16(gg[0], gg[1]), cvt_pk_bf16(gg[2], gg[3])};
;                         if (ai == 0 && m == 0 && wr == 0 && fr < 2) { *(f32x4*)(HALO_A + (size_t)(u.pm * 2 + fr) * 2816 + colt + 4 * n) = a; *(f32x4*)(HALO_U + (size_t)(u.pm * 2 + fr) * 2816 + colt + 4 * n) = uu; }
;                         if (ai == 1 && m == 3 && wr == 1 && fr >= 14) { *(f32x4*)(LASTA + (size_t)(u.pm * 2 + fr - 14) * 2816 + colt + 4 * n) = a;
;                             if ((u.pm & 31) == 31) *(f32x4*)(ocp + (size_t)((u.pm >> 5) * 2 + fr - 14) * 2816 + colt + 4 * n) = a; }
	v_pk_fma_f32 v[152:153], v[222:223], v[172:173], v[152:153]
	s_nop 0
	v_pk_fma_f32 v[152:153], v[154:155], v[226:227], v[152:153]
	s_nop 0
	v_mul_f32_e32 v172, 0xbfb8aa3b, v152
	v_mul_f32_e32 v173, 0xbfb8aa3b, v153
	v_exp_f32_e32 v172, v172
	v_exp_f32_e32 v173, v173
	v_add_f32_e32 v172, 1.0, v172
	v_add_f32_e32 v173, 1.0, v173
	v_rcp_f32_e32 v172, v172
	v_rcp_f32_e32 v173, v173
	s_nop 0
	v_pk_mul_f32 v[152:153], v[152:153], v[172:173]
	s_nop 0
	v_pk_mul_f32 v[152:153], v[156:157], v[152:153]
	v_cndmask_b32_e64 v156, v150, v146, s[8:9]
	v_cndmask_b32_e64 v146, v150, v146, s[6:7]
	v_cndmask_b32_e64 v157, v151, v147, s[8:9]
	v_cndmask_b32_e64 v147, v151, v147, s[6:7]
	ds_bpermute_b32 v146, v208, v146
	ds_bpermute_b32 v147, v208, v147
	ds_bpermute_b32 v156, v209, v156
	ds_bpermute_b32 v157, v209, v157
	s_waitcnt lgkmcnt(2)
	v_pk_fma_f32 v[146:147], v[220:221], v[146:147], v[246:247]
	s_waitcnt lgkmcnt(0)
	v_pk_fma_f32 v[146:147], v[224:225], v[156:157], v[146:147]
	s_nop 0
	v_pk_fma_f32 v[146:147], v[150:151], v[228:229], v[146:147]
	s_nop 0
	v_mul_f32_e32 v156, 0xbfb8aa3b, v146
	v_mul_f32_e32 v157, 0xbfb8aa3b, v147
	v_exp_f32_e32 v156, v156
	v_exp_f32_e32 v157, v157
	v_add_f32_e32 v156, 1.0, v156
	v_add_f32_e32 v157, 1.0, v157
	v_rcp_f32_e32 v156, v156
	v_rcp_f32_e32 v157, v157
	s_nop 0
	v_pk_mul_f32 v[146:147], v[146:147], v[156:157]
	s_nop 0
	v_pk_mul_f32 v[146:147], v[148:149], v[146:147]
	v_cvt_pk_bf16_f32 v148, v152, v153
	v_cvt_pk_bf16_f32 v149, v146, v147
	v_pk_mul_f32 v[146:147], v[34:35], v[170:171]
	v_mov_b32_e32 v152, v170
	v_mov_b32_e32 v153, v170
	v_pk_mul_f32 v[156:157], v[2:3], v[170:171]
	v_cndmask_b32_e64 v170, v146, v154, s[8:9]
	v_cndmask_b32_e64 v154, v146, v154, s[6:7]
	v_cndmask_b32_e64 v171, v147, v155, s[8:9]
	v_cndmask_b32_e64 v155, v147, v155, s[6:7]
	ds_bpermute_b32 v154, v208, v154
	ds_bpermute_b32 v155, v208, v155
	ds_bpermute_b32 v170, v209, v170
	ds_bpermute_b32 v171, v209, v171
	global_store_dwordx2 v[192:193], v[148:149], off offset:8
	v_pk_mul_f32 v[148:149], v[36:37], v[152:153]
	s_waitcnt lgkmcnt(2)
	v_pk_fma_f32 v[218:219], v[218:219], v[154:155], v[244:245]
	v_pk_mul_f32 v[152:153], v[4:5], v[152:153]
	s_waitcnt lgkmcnt(0)
	v_pk_fma_f32 v[218:219], v[222:223], v[170:171], v[218:219]
	s_nop 0
	v_pk_fma_f32 v[218:219], v[146:147], v[226:227], v[218:219]
	v_cndmask_b32_e64 v227, v149, v151, s[6:7]
	v_mul_f32_e32 v222, 0xbfb8aa3b, v218
	v_mul_f32_e32 v223, 0xbfb8aa3b, v219
	v_exp_f32_e32 v222, v222
	v_exp_f32_e32 v223, v223
	ds_bpermute_b32 v227, v208, v227
	v_add_f32_e32 v222, 1.0, v222
	v_add_f32_e32 v223, 1.0, v223
	v_rcp_f32_e32 v222, v222
	v_rcp_f32_e32 v223, v223
	s_nop 0
	v_pk_mul_f32 v[218:219], v[218:219], v[222:223]
	v_cndmask_b32_e64 v223, v148, v150, s[6:7]
	v_cndmask_b32_e64 v222, v148, v150, s[8:9]
	ds_bpermute_b32 v226, v208, v223
	v_cndmask_b32_e64 v223, v149, v151, s[8:9]
	ds_bpermute_b32 v222, v209, v222
	ds_bpermute_b32 v223, v209, v223
	v_pk_mul_f32 v[218:219], v[156:157], v[218:219]
	s_waitcnt lgkmcnt(2)
	v_pk_fma_f32 v[220:221], v[220:221], v[226:227], v[246:247]
	v_cvt_pk_bf16_f32 v218, v218, v219
	s_waitcnt lgkmcnt(0)
	v_pk_fma_f32 v[220:221], v[224:225], v[222:223], v[220:221]
	s_nop 0
	v_pk_fma_f32 v[220:221], v[148:149], v[228:229], v[220:221]
	s_nop 0
	v_mul_f32_e32 v222, 0xbfb8aa3b, v220
	v_mul_f32_e32 v223, 0xbfb8aa3b, v221
	v_exp_f32_e32 v222, v222
	v_exp_f32_e32 v223, v223
	v_add_f32_e32 v222, 1.0, v222
	v_add_f32_e32 v223, 1.0, v223
	v_rcp_f32_e32 v222, v222
	v_rcp_f32_e32 v223, v223
	s_nop 0
	v_pk_mul_f32 v[220:221], v[220:221], v[222:223]
	s_nop 0
	v_pk_mul_f32 v[220:221], v[152:153], v[220:221]
	s_nop 0
	v_cvt_pk_bf16_f32 v219, v220, v221
	global_store_dwordx2 v[186:187], v[218:219], off offset:8
	s_and_saveexec_b64 s[6:7], s[12:13]
	s_cbranch_execz .LBB0_1017
	v_readlane_b32 s8, v255, 20
	v_readlane_b32 s9, v255, 21
	s_nop 1
	v_mov_b64_e32 v[218:219], s[8:9]
	v_mad_i64_i32 v[218:219], s[8:9], v211, s48, v[218:219]
	s_and_b32 s8, s34, 31
	v_lshl_add_u64 v[218:219], v[168:169], 2, v[218:219]
	s_cmp_eq_u32 s8, 31
	s_mov_b64 s[8:9], s[10:11]
	global_store_dwordx4 v[218:219], v[146:149], off offset:16
	s_cbranch_scc0 .LBB0_1016
	s_ashr_i32 s8, s34, 4
	s_and_b32 s8, s8, -2
	v_add_u32_e32 v242, s8, v210
	s_or_b64 s[8:9], s[10:11], exec
